# residual GEMM epilogues (out-proj, down-proj): residual rows prefetched 3 row-groups ahead into free registers, adds read them directly (no register copies), counted waits
# speedup vs baseline: 1.0484x; 1.0004x over previous
.LBB0_568:
	s_add_u32 s36, s28, 0xfffc0080
	s_addc_u32 s37, s29, -1
	s_add_i32 s68, s44, 0x120
	s_cmp_eq_u32 s67, 12
	s_cselect_b32 s39, s23, s37
	s_cselect_b32 s38, s61, s36
	v_add_u32_e32 v142, s68, v145
	s_cselect_b32 s37, s21, s66
	s_cselect_b32 s36, s62, s63
	s_add_i32 s70, s45, 0x120
	ds_read_b128 v[138:141], v142
	ds_read_b128 v[148:151], v142 offset:1024
	ds_read_b128 v[152:155], v142 offset:2048
	ds_read_b128 v[156:159], v142 offset:3072
	v_add_u32_e32 v142, s70, v145
	ds_read_b128 v[200:203], v142
	ds_read_b128 v[204:207], v142 offset:1024
	ds_read_b128 v[208:211], v142 offset:2048
	ds_read_b128 v[212:215], v142 offset:3072
	v_lshl_add_u64 v[142:143], s[28:29], 0, v[134:135]
	s_add_i32 m0, s52, 0xc000
	ds_read_b128 v[216:219], v147
	ds_read_b128 v[220:223], v147 offset:1024
	ds_read_b128 v[224:227], v147 offset:2048
	ds_read_b128 v[228:231], v147 offset:3072
	ds_read_b128 v[232:235], v147 offset:4096
	ds_read_b128 v[236:239], v147 offset:5120
	ds_read_b128 v[240:243], v147 offset:6144
	ds_read_b128 v[244:247], v147 offset:7168
	global_load_lds_dwordx4 v[142:143], off
	v_lshl_add_u64 v[142:143], s[28:29], 0, v[136:137]
	s_add_i32 m0, s52, 0xe000
	s_nop 0
	global_load_lds_dwordx4 v[142:143], off
	s_waitcnt vmcnt(8)
	s_waitcnt lgkmcnt(0)
	s_barrier
	s_setprio 1
	s_waitcnt lgkmcnt(0)
	v_mfma_f32_16x16x32_bf16 v[124:127], v[138:141], v[216:219], v[124:127]
	v_mfma_f32_16x16x32_bf16 v[120:123], v[152:155], v[216:219], v[120:123]
	v_mfma_f32_16x16x32_bf16 v[108:111], v[138:141], v[224:227], v[108:111]
	v_mfma_f32_16x16x32_bf16 v[104:107], v[152:155], v[224:227], v[104:107]
	v_mfma_f32_16x16x32_bf16 v[92:95], v[138:141], v[232:235], v[92:95]
	v_mfma_f32_16x16x32_bf16 v[88:91], v[152:155], v[232:235], v[88:91]
	v_mfma_f32_16x16x32_bf16 v[76:79], v[138:141], v[240:243], v[76:79]
	v_mfma_f32_16x16x32_bf16 v[72:75], v[152:155], v[240:243], v[72:75]
	v_mfma_f32_16x16x32_bf16 v[124:127], v[148:151], v[220:223], v[124:127]
	v_mfma_f32_16x16x32_bf16 v[120:123], v[156:159], v[220:223], v[120:123]
	v_mfma_f32_16x16x32_bf16 v[108:111], v[148:151], v[228:231], v[108:111]
	v_mfma_f32_16x16x32_bf16 v[104:107], v[156:159], v[228:231], v[104:107]
	v_mfma_f32_16x16x32_bf16 v[92:95], v[148:151], v[236:239], v[92:95]
	v_mfma_f32_16x16x32_bf16 v[88:91], v[156:159], v[236:239], v[88:91]
	v_mfma_f32_16x16x32_bf16 v[76:79], v[148:151], v[244:247], v[76:79]
	v_mfma_f32_16x16x32_bf16 v[72:75], v[156:159], v[244:247], v[72:75]
	s_setprio 0
	s_setprio 1
	v_mfma_f32_16x16x32_bf16 v[116:119], v[200:203], v[216:219], v[116:119]
	v_mfma_f32_16x16x32_bf16 v[112:115], v[208:211], v[216:219], v[112:115]
	v_mfma_f32_16x16x32_bf16 v[100:103], v[200:203], v[224:227], v[100:103]
	v_mfma_f32_16x16x32_bf16 v[96:99], v[208:211], v[224:227], v[96:99]
	v_mfma_f32_16x16x32_bf16 v[84:87], v[200:203], v[232:235], v[84:87]
	v_mfma_f32_16x16x32_bf16 v[80:83], v[208:211], v[232:235], v[80:83]
	v_mfma_f32_16x16x32_bf16 v[68:71], v[200:203], v[240:243], v[68:71]
	v_mfma_f32_16x16x32_bf16 v[64:67], v[208:211], v[240:243], v[64:67]
	v_mfma_f32_16x16x32_bf16 v[116:119], v[204:207], v[220:223], v[116:119]
	v_mfma_f32_16x16x32_bf16 v[112:115], v[212:215], v[220:223], v[112:115]
	v_mfma_f32_16x16x32_bf16 v[100:103], v[204:207], v[228:231], v[100:103]
	v_mfma_f32_16x16x32_bf16 v[96:99], v[212:215], v[228:231], v[96:99]
	v_mfma_f32_16x16x32_bf16 v[84:87], v[204:207], v[236:239], v[84:87]
	v_mfma_f32_16x16x32_bf16 v[80:83], v[212:215], v[236:239], v[80:83]
	v_mfma_f32_16x16x32_bf16 v[68:71], v[204:207], v[244:247], v[68:71]
	v_mfma_f32_16x16x32_bf16 v[64:67], v[212:215], v[244:247], v[64:67]
	s_setprio 0
	s_barrier
	s_add_i32 s68, s68, s49
	v_lshl_add_u64 v[142:143], s[36:37], 0, v[160:161]
	s_mov_b32 m0, s68
	ds_read_b128 v[216:219], v147 offset:16384
	ds_read_b128 v[220:223], v147 offset:17408
	ds_read_b128 v[224:227], v147 offset:18432
	ds_read_b128 v[228:231], v147 offset:19456
	ds_read_b128 v[232:235], v147 offset:20480
	ds_read_b128 v[236:239], v147 offset:21504
	ds_read_b128 v[240:243], v147 offset:22528
	ds_read_b128 v[244:247], v147 offset:23552
	global_load_lds_dwordx4 v[142:143], off
	s_add_i32 m0, s68, 0x2000
	s_add_u32 s68, s36, 0x40000
	v_lshl_add_u64 v[170:171], s[36:37], 0, v[128:129]
	s_addc_u32 s69, s37, 0
	s_add_i32 s70, s70, s49
	global_load_lds_dwordx4 v[170:171], off
	v_lshl_add_u64 v[174:175], s[68:69], 0, v[160:161]
	s_mov_b32 m0, s70
	v_lshl_add_u64 v[198:199], s[38:39], 0, v[130:131]
	global_load_lds_dwordx4 v[174:175], off
	v_lshl_add_u64 v[174:175], s[68:69], 0, v[128:129]
	s_add_i32 m0, s70, 0x2000
	s_nop 0
	global_load_lds_dwordx4 v[174:175], off
	v_lshl_add_u64 v[174:175], s[38:39], 0, v[132:133]
	s_mov_b32 m0, s52
	s_nop 0
	global_load_lds_dwordx4 v[174:175], off
	s_mov_b32 m0, s53
	s_nop 0
	global_load_lds_dwordx4 v[198:199], off
	s_waitcnt vmcnt(8)
	s_waitcnt lgkmcnt(0)
	s_barrier
	s_setprio 1
	s_waitcnt lgkmcnt(0)
	v_mfma_f32_16x16x32_bf16 v[60:63], v[138:141], v[216:219], v[60:63]
	v_mfma_f32_16x16x32_bf16 v[56:59], v[152:155], v[216:219], v[56:59]
	v_mfma_f32_16x16x32_bf16 v[44:47], v[138:141], v[224:227], v[44:47]
	v_mfma_f32_16x16x32_bf16 v[40:43], v[152:155], v[224:227], v[40:43]
	v_mfma_f32_16x16x32_bf16 v[28:31], v[138:141], v[232:235], v[28:31]
	v_mfma_f32_16x16x32_bf16 v[24:27], v[152:155], v[232:235], v[24:27]
	v_mfma_f32_16x16x32_bf16 v[12:15], v[138:141], v[240:243], v[12:15]
	v_mfma_f32_16x16x32_bf16 v[8:11], v[152:155], v[240:243], v[8:11]
	v_mfma_f32_16x16x32_bf16 v[60:63], v[148:151], v[220:223], v[60:63]
	v_mfma_f32_16x16x32_bf16 v[56:59], v[156:159], v[220:223], v[56:59]
	v_mfma_f32_16x16x32_bf16 v[44:47], v[148:151], v[228:231], v[44:47]
	v_mfma_f32_16x16x32_bf16 v[40:43], v[156:159], v[228:231], v[40:43]
	v_mfma_f32_16x16x32_bf16 v[28:31], v[148:151], v[236:239], v[28:31]
	v_mfma_f32_16x16x32_bf16 v[24:27], v[156:159], v[236:239], v[24:27]
	v_mfma_f32_16x16x32_bf16 v[12:15], v[148:151], v[244:247], v[12:15]
	v_mfma_f32_16x16x32_bf16 v[8:11], v[156:159], v[244:247], v[8:11]
	s_setprio 0
	s_setprio 1
	v_mfma_f32_16x16x32_bf16 v[52:55], v[200:203], v[216:219], v[52:55]
	v_mfma_f32_16x16x32_bf16 v[48:51], v[208:211], v[216:219], v[48:51]
	v_mfma_f32_16x16x32_bf16 v[36:39], v[200:203], v[224:227], v[36:39]
	v_mfma_f32_16x16x32_bf16 v[32:35], v[208:211], v[224:227], v[32:35]
	v_mfma_f32_16x16x32_bf16 v[20:23], v[200:203], v[232:235], v[20:23]
	v_mfma_f32_16x16x32_bf16 v[16:19], v[208:211], v[232:235], v[16:19]
	v_mfma_f32_16x16x32_bf16 v[4:7], v[200:203], v[240:243], v[4:7]
	v_mfma_f32_16x16x32_bf16 v[0:3], v[208:211], v[240:243], v[0:3]
	v_mfma_f32_16x16x32_bf16 v[52:55], v[204:207], v[220:223], v[52:55]
	v_mfma_f32_16x16x32_bf16 v[48:51], v[212:215], v[220:223], v[48:51]
	v_mfma_f32_16x16x32_bf16 v[36:39], v[204:207], v[228:231], v[36:39]
	v_mfma_f32_16x16x32_bf16 v[32:35], v[212:215], v[228:231], v[32:35]
	v_mfma_f32_16x16x32_bf16 v[20:23], v[204:207], v[236:239], v[20:23]
	v_mfma_f32_16x16x32_bf16 v[16:19], v[212:215], v[236:239], v[16:19]
	v_mfma_f32_16x16x32_bf16 v[4:7], v[204:207], v[244:247], v[4:7]
	v_mfma_f32_16x16x32_bf16 v[0:3], v[212:215], v[244:247], v[0:3]
	s_setprio 0
	s_barrier
	s_add_i32 s68, s46, 0x120
	s_add_i32 s69, s47, 0x120
	v_add_u32_e32 v156, s68, v145
	v_add_u32_e32 v172, s69, v145
	ds_read_b128 v[138:141], v156
	ds_read_b128 v[148:151], v156 offset:1024
	ds_read_b128 v[152:155], v156 offset:2048
	ds_read_b128 v[156:159], v156 offset:3072
	ds_read_b128 v[200:203], v172
	ds_read_b128 v[204:207], v172 offset:1024
	ds_read_b128 v[208:211], v172 offset:2048
	ds_read_b128 v[212:215], v172 offset:3072
	s_add_u32 s38, s38, 0x40000
	s_addc_u32 s39, s39, 0
	s_mov_b32 m0, s56
	v_lshl_add_u64 v[248:249], s[38:39], 0, v[132:133]
	ds_read_b128 v[216:219], v147 offset:32768
	ds_read_b128 v[220:223], v147 offset:33792
	ds_read_b128 v[224:227], v147 offset:34816
	ds_read_b128 v[228:231], v147 offset:35840
	ds_read_b128 v[232:235], v147 offset:36864
	ds_read_b128 v[236:239], v147 offset:37888
	ds_read_b128 v[240:243], v147 offset:38912
	ds_read_b128 v[244:247], v147 offset:39936
	global_load_lds_dwordx4 v[248:249], off
	v_lshl_add_u64 v[248:249], s[38:39], 0, v[130:131]
	s_mov_b32 m0, s57
	s_nop 0
	global_load_lds_dwordx4 v[248:249], off
	s_waitcnt vmcnt(8)
	s_waitcnt lgkmcnt(0)
	s_barrier
	s_setprio 1
	s_waitcnt lgkmcnt(0)
	v_mfma_f32_16x16x32_bf16 v[124:127], v[138:141], v[216:219], v[124:127]
	v_mfma_f32_16x16x32_bf16 v[120:123], v[152:155], v[216:219], v[120:123]
	v_mfma_f32_16x16x32_bf16 v[108:111], v[138:141], v[224:227], v[108:111]
	v_mfma_f32_16x16x32_bf16 v[104:107], v[152:155], v[224:227], v[104:107]
	v_mfma_f32_16x16x32_bf16 v[92:95], v[138:141], v[232:235], v[92:95]
	v_mfma_f32_16x16x32_bf16 v[88:91], v[152:155], v[232:235], v[88:91]
	v_mfma_f32_16x16x32_bf16 v[76:79], v[138:141], v[240:243], v[76:79]
	v_mfma_f32_16x16x32_bf16 v[72:75], v[152:155], v[240:243], v[72:75]
	v_mfma_f32_16x16x32_bf16 v[124:127], v[148:151], v[220:223], v[124:127]
	v_mfma_f32_16x16x32_bf16 v[120:123], v[156:159], v[220:223], v[120:123]
	v_mfma_f32_16x16x32_bf16 v[108:111], v[148:151], v[228:231], v[108:111]
	v_mfma_f32_16x16x32_bf16 v[104:107], v[156:159], v[228:231], v[104:107]
	v_mfma_f32_16x16x32_bf16 v[92:95], v[148:151], v[236:239], v[92:95]
	v_mfma_f32_16x16x32_bf16 v[88:91], v[156:159], v[236:239], v[88:91]
	v_mfma_f32_16x16x32_bf16 v[76:79], v[148:151], v[244:247], v[76:79]
	v_mfma_f32_16x16x32_bf16 v[72:75], v[156:159], v[244:247], v[72:75]
	s_setprio 0
	s_setprio 1
	v_mfma_f32_16x16x32_bf16 v[116:119], v[200:203], v[216:219], v[116:119]
	v_mfma_f32_16x16x32_bf16 v[112:115], v[208:211], v[216:219], v[112:115]
	v_mfma_f32_16x16x32_bf16 v[100:103], v[200:203], v[224:227], v[100:103]
	v_mfma_f32_16x16x32_bf16 v[96:99], v[208:211], v[224:227], v[96:99]
	v_mfma_f32_16x16x32_bf16 v[84:87], v[200:203], v[232:235], v[84:87]
	v_mfma_f32_16x16x32_bf16 v[80:83], v[208:211], v[232:235], v[80:83]
	v_mfma_f32_16x16x32_bf16 v[68:71], v[200:203], v[240:243], v[68:71]
	v_mfma_f32_16x16x32_bf16 v[64:67], v[208:211], v[240:243], v[64:67]
	v_mfma_f32_16x16x32_bf16 v[116:119], v[204:207], v[220:223], v[116:119]
	v_mfma_f32_16x16x32_bf16 v[112:115], v[212:215], v[220:223], v[112:115]
	v_mfma_f32_16x16x32_bf16 v[100:103], v[204:207], v[228:231], v[100:103]
	v_mfma_f32_16x16x32_bf16 v[96:99], v[212:215], v[228:231], v[96:99]
	v_mfma_f32_16x16x32_bf16 v[84:87], v[204:207], v[236:239], v[84:87]
	v_mfma_f32_16x16x32_bf16 v[80:83], v[212:215], v[236:239], v[80:83]
	v_mfma_f32_16x16x32_bf16 v[68:71], v[204:207], v[244:247], v[68:71]
	v_mfma_f32_16x16x32_bf16 v[64:67], v[212:215], v[244:247], v[64:67]
	s_setprio 0
	s_barrier
	s_add_i32 s38, s68, s49
	v_lshl_add_u64 v[142:143], v[142:143], 0, s[88:89]
	s_mov_b32 m0, s38
	ds_read_b128 v[216:219], v147 offset:49152
	ds_read_b128 v[220:223], v147 offset:50176
	ds_read_b128 v[224:227], v147 offset:51200
	ds_read_b128 v[228:231], v147 offset:52224
	ds_read_b128 v[232:235], v147 offset:53248
	ds_read_b128 v[236:239], v147 offset:54272
	ds_read_b128 v[240:243], v147 offset:55296
	ds_read_b128 v[244:247], v147 offset:56320
	global_load_lds_dwordx4 v[142:143], off
	s_add_i32 m0, s38, 0x2000
	s_add_u32 s36, s36, 0x40080
	v_lshl_add_u64 v[142:143], v[170:171], 0, s[88:89]
	s_addc_u32 s37, s37, 0
	s_add_i32 s38, s69, s49
	global_load_lds_dwordx4 v[142:143], off
	v_lshl_add_u64 v[142:143], s[36:37], 0, v[160:161]
	s_mov_b32 m0, s38
	s_nop 0
	global_load_lds_dwordx4 v[142:143], off
	v_lshl_add_u64 v[142:143], s[36:37], 0, v[128:129]
	s_add_i32 m0, s38, 0x2000
	s_nop 0
	global_load_lds_dwordx4 v[142:143], off
	v_lshl_add_u64 v[142:143], v[174:175], 0, s[88:89]
	s_mov_b32 m0, s58
	s_nop 0
	global_load_lds_dwordx4 v[142:143], off
	v_lshl_add_u64 v[142:143], v[198:199], 0, s[88:89]
	s_mov_b32 m0, s59
	s_nop 0
	global_load_lds_dwordx4 v[142:143], off
	s_waitcnt vmcnt(8)
	s_waitcnt lgkmcnt(0)
	s_barrier
	s_setprio 1
	s_waitcnt lgkmcnt(0)
	v_mfma_f32_16x16x32_bf16 v[60:63], v[138:141], v[216:219], v[60:63]
	v_mfma_f32_16x16x32_bf16 v[56:59], v[152:155], v[216:219], v[56:59]
	v_mfma_f32_16x16x32_bf16 v[44:47], v[138:141], v[224:227], v[44:47]
	v_mfma_f32_16x16x32_bf16 v[40:43], v[152:155], v[224:227], v[40:43]
	v_mfma_f32_16x16x32_bf16 v[28:31], v[138:141], v[232:235], v[28:31]
	v_mfma_f32_16x16x32_bf16 v[24:27], v[152:155], v[232:235], v[24:27]
	v_mfma_f32_16x16x32_bf16 v[12:15], v[138:141], v[240:243], v[12:15]
	v_mfma_f32_16x16x32_bf16 v[8:11], v[152:155], v[240:243], v[8:11]
	v_mfma_f32_16x16x32_bf16 v[60:63], v[148:151], v[220:223], v[60:63]
	v_mfma_f32_16x16x32_bf16 v[56:59], v[156:159], v[220:223], v[56:59]
	v_mfma_f32_16x16x32_bf16 v[44:47], v[148:151], v[228:231], v[44:47]
	v_mfma_f32_16x16x32_bf16 v[40:43], v[156:159], v[228:231], v[40:43]
	v_mfma_f32_16x16x32_bf16 v[28:31], v[148:151], v[236:239], v[28:31]
	v_mfma_f32_16x16x32_bf16 v[24:27], v[156:159], v[236:239], v[24:27]
	v_mfma_f32_16x16x32_bf16 v[12:15], v[148:151], v[244:247], v[12:15]
	v_mfma_f32_16x16x32_bf16 v[8:11], v[156:159], v[244:247], v[8:11]
	s_setprio 0
	s_setprio 1
	v_mfma_f32_16x16x32_bf16 v[52:55], v[200:203], v[216:219], v[52:55]
	v_mfma_f32_16x16x32_bf16 v[48:51], v[208:211], v[216:219], v[48:51]
	v_mfma_f32_16x16x32_bf16 v[36:39], v[200:203], v[224:227], v[36:39]
	v_mfma_f32_16x16x32_bf16 v[32:35], v[208:211], v[224:227], v[32:35]
	v_mfma_f32_16x16x32_bf16 v[20:23], v[200:203], v[232:235], v[20:23]
	v_mfma_f32_16x16x32_bf16 v[16:19], v[208:211], v[232:235], v[16:19]
	v_mfma_f32_16x16x32_bf16 v[4:7], v[200:203], v[240:243], v[4:7]
	v_mfma_f32_16x16x32_bf16 v[0:3], v[208:211], v[240:243], v[0:3]
	v_mfma_f32_16x16x32_bf16 v[52:55], v[204:207], v[220:223], v[52:55]
	v_mfma_f32_16x16x32_bf16 v[48:51], v[212:215], v[220:223], v[48:51]
	v_mfma_f32_16x16x32_bf16 v[36:39], v[204:207], v[228:231], v[36:39]
	v_mfma_f32_16x16x32_bf16 v[32:35], v[212:215], v[228:231], v[32:35]
	v_mfma_f32_16x16x32_bf16 v[20:23], v[204:207], v[236:239], v[20:23]
	v_mfma_f32_16x16x32_bf16 v[16:19], v[212:215], v[236:239], v[16:19]
	v_mfma_f32_16x16x32_bf16 v[4:7], v[204:207], v[244:247], v[4:7]
	v_mfma_f32_16x16x32_bf16 v[0:3], v[212:215], v[244:247], v[0:3]
	s_setprio 0
	s_barrier
	s_add_i32 s67, s67, 2
	s_add_u32 s28, s28, 0x100
	s_addc_u32 s29, s29, 0
	s_add_u32 s63, s63, 0x100
	s_addc_u32 s66, s66, 0
	s_cmp_gt_u32 s67, 13
	s_cbranch_scc0 .LBB0_568
	v_lshl_add_u32 v142, s51, 8, v144
	v_lshl_or_b32 v140, s1, 8, v146
	v_ashrrev_i32_e32 v143, 31, v142
	v_ashrrev_i32_e32 v141, 31, v140
	v_lshlrev_b64 v[138:139], 10, v[142:143]
	v_lshl_add_u64 v[138:139], v[138:139], 0, v[140:141]
	v_lshlrev_b64 v[156:157], 2, v[138:139]
	v_lshl_add_u64 v[158:159], s[16:17], 0, v[156:157]
	v_mov_b32_e32 v248, v158
	v_mov_b32_e32 v249, v159
	global_load_dwordx4 v[200:203], v[248:249], off
	global_load_dwordx4 v[204:207], v[248:249], off offset:16
	global_load_dwordx4 v[208:211], v[248:249], off offset:512
	global_load_dwordx4 v[212:215], v[248:249], off offset:528
	s_mov_b64 s[98:99], 0x10000
	v_lshl_add_u64 v[250:251], v[248:249], 0, s[98:99]
	global_load_dwordx4 v[216:219], v[250:251], off
	global_load_dwordx4 v[220:223], v[250:251], off offset:16
	global_load_dwordx4 v[224:227], v[250:251], off offset:512
	global_load_dwordx4 v[228:231], v[250:251], off offset:528
	s_mov_b64 s[98:99], 0x20000
	v_lshl_add_u64 v[250:251], v[248:249], 0, s[98:99]
	global_load_dwordx4 v[232:235], v[250:251], off
	global_load_dwordx4 v[236:239], v[250:251], off offset:16
	global_load_dwordx4 v[240:243], v[250:251], off offset:512
	global_load_dwordx4 v[244:247], v[250:251], off offset:528
	s_waitcnt vmcnt(8)
	v_pk_add_f32 v[122:123], v[122:123], v[206:207]
	v_pk_add_f32 v[126:127], v[126:127], v[202:203]
	v_pk_add_f32 v[124:125], v[124:125], v[200:201]
	v_lshl_add_u64 v[152:153], s[12:13], 0, v[156:157]
	v_pk_add_f32 v[120:121], v[120:121], v[204:205]
	global_store_dwordx4 v[152:153], v[124:127], off
	global_store_dwordx4 v[152:153], v[120:123], off offset:16
	v_cvt_pk_bf16_f32 v148, v124, v125
	v_mul_f32_e32 v125, v125, v125
	v_fmac_f32_e32 v125, v124, v124
	v_mul_f32_e32 v124, v127, v127
	v_cvt_pk_bf16_f32 v150, v120, v121
	v_fmac_f32_e32 v124, v126, v126
	v_mul_f32_e32 v121, v121, v121
	v_add_f32_e32 v124, v125, v124
	v_fmac_f32_e32 v121, v120, v120
	v_cvt_pk_bf16_f32 v149, v126, v127
	v_cvt_pk_bf16_f32 v151, v122, v123
	v_lshl_add_u64 v[154:155], v[138:139], 1, s[18:19]
	v_add_f32_e32 v120, v124, v121
	v_mul_f32_e32 v121, v123, v123
	global_store_dwordx4 v[154:155], v[148:151], off
	v_fmac_f32_e32 v121, v122, v122
	s_nop 0
	v_add_f32_e32 v148, v121, v120
	v_pk_add_f32 v[114:115], v[114:115], v[214:215]
	v_pk_add_f32 v[118:119], v[118:119], v[210:211]
	v_pk_add_f32 v[116:117], v[116:117], v[208:209]
	v_pk_add_f32 v[112:113], v[112:113], v[212:213]
	global_store_dwordx4 v[152:153], v[116:119], off offset:512
	global_store_dwordx4 v[152:153], v[112:115], off offset:528
	v_cvt_pk_bf16_f32 v123, v114, v115
	v_cvt_pk_bf16_f32 v120, v116, v117
	v_mul_f32_e32 v115, v115, v115
	v_fmac_f32_e32 v115, v114, v114
	v_mul_f32_e32 v114, v117, v117
	v_fmac_f32_e32 v114, v116, v116
	v_mul_f32_e32 v116, v119, v119
	v_cvt_pk_bf16_f32 v122, v112, v113
	v_fmac_f32_e32 v116, v118, v118
	v_mul_f32_e32 v113, v113, v113
	v_add_f32_e32 v114, v114, v116
	v_fmac_f32_e32 v113, v112, v112
	v_add_f32_e32 v112, v114, v113
	v_add_f32_e32 v112, v115, v112
	v_add_f32_e32 v112, v148, v112
	ds_bpermute_b32 v113, v180, v112
	v_cvt_pk_bf16_f32 v121, v118, v119
	global_store_dwordx4 v[154:155], v[120:123], off offset:256
	s_waitcnt lgkmcnt(0)
	v_add_f32_e32 v114, v112, v113
	ds_bpermute_b32 v115, v181, v114
	v_lshl_add_u64 v[112:113], v[142:143], 3, s[14:15]
	s_and_saveexec_b64 s[28:29], s[8:9]
	s_cbranch_execz .LBB0_571
	s_waitcnt lgkmcnt(0)
	v_add_f32_e32 v114, v114, v115
	v_fma_f32 v114, v114, s65, 0.5
	v_trunc_f32_e32 v114, v114
	v_mul_f32_e32 v115, 0x2f800000, v114
	v_floor_f32_e32 v115, v115
	v_fmac_f32_e32 v114, 0xcf800000, v115
	v_cvt_u32_f32_e32 v114, v114
	v_cvt_u32_f32_e32 v115, v115
	global_atomic_add_x2 v[112:113], v[114:115], off
.LBB0_571:
	s_or_b64 exec, exec, s[28:29]
	v_or_b32_e32 v114, 16, v142
	s_waitcnt lgkmcnt(0)
	v_ashrrev_i32_e32 v115, 31, v114
	v_lshlrev_b64 v[114:115], 10, v[114:115]
	v_lshl_add_u64 v[122:123], v[114:115], 0, v[140:141]
	v_lshlrev_b64 v[124:125], 2, v[122:123]
	v_lshl_add_u64 v[126:127], s[16:17], 0, v[124:125]
	s_mov_b64 s[98:99], 0x30000
	v_lshl_add_u64 v[250:251], v[248:249], 0, s[98:99]
	global_load_dwordx4 v[200:203], v[250:251], off
	global_load_dwordx4 v[204:207], v[250:251], off offset:16
	global_load_dwordx4 v[208:211], v[250:251], off offset:512
	global_load_dwordx4 v[212:215], v[250:251], off offset:528
	s_waitcnt vmcnt(12)
	v_lshl_add_u64 v[122:123], v[122:123], 1, s[18:19]
	v_lshl_add_u64 v[124:125], s[12:13], 0, v[124:125]
	v_pk_add_f32 v[110:111], v[110:111], v[218:219]
	v_pk_add_f32 v[108:109], v[108:109], v[216:217]
	v_pk_add_f32 v[106:107], v[106:107], v[222:223]
	v_pk_add_f32 v[104:105], v[104:105], v[220:221]
	v_cvt_pk_bf16_f32 v114, v108, v109
	v_cvt_pk_bf16_f32 v115, v110, v111
	v_cvt_pk_bf16_f32 v116, v104, v105
	v_cvt_pk_bf16_f32 v117, v106, v107
	global_store_dwordx4 v[124:125], v[108:111], off
	global_store_dwordx4 v[124:125], v[104:107], off offset:16
	global_store_dwordx4 v[122:123], v[114:117], off
	s_nop 0
	v_mul_f32_e32 v109, v109, v109
	v_mul_f32_e32 v111, v111, v111
	v_mul_f32_e32 v105, v105, v105
	v_fmac_f32_e32 v109, v108, v108
	v_fmac_f32_e32 v111, v110, v110
	v_mul_f32_e32 v107, v107, v107
	v_fmac_f32_e32 v105, v104, v104
	v_add_f32_e32 v104, v109, v111
	v_fmac_f32_e32 v107, v106, v106
	v_add_f32_e32 v104, v104, v105
	v_add_f32_e32 v108, v107, v104
	v_pk_add_f32 v[102:103], v[102:103], v[226:227]
	v_pk_add_f32 v[100:101], v[100:101], v[224:225]
	v_pk_add_f32 v[106:107], v[98:99], v[230:231]
	v_pk_add_f32 v[104:105], v[96:97], v[228:229]
	v_mul_f32_e32 v97, v101, v101
	v_mul_f32_e32 v98, v103, v103
	v_mul_f32_e32 v99, v105, v105
	v_fmac_f32_e32 v97, v100, v100
	v_fmac_f32_e32 v98, v102, v102
	v_mul_f32_e32 v96, v107, v107
	v_add_f32_e32 v97, v97, v98
	v_fmac_f32_e32 v99, v104, v104
	v_fmac_f32_e32 v96, v106, v106
	v_add_f32_e32 v97, v97, v99
	v_add_f32_e32 v96, v96, v97
	v_add_f32_e32 v96, v108, v96
	ds_bpermute_b32 v97, v180, v96
	global_store_dwordx4 v[124:125], v[100:103], off offset:512
	global_store_dwordx4 v[124:125], v[104:107], off offset:528
	v_cvt_pk_bf16_f32 v98, v100, v101
	v_cvt_pk_bf16_f32 v99, v102, v103
	v_cvt_pk_bf16_f32 v100, v104, v105
	s_waitcnt lgkmcnt(0)
	v_add_f32_e32 v96, v96, v97
	ds_bpermute_b32 v97, v181, v96
	v_cvt_pk_bf16_f32 v101, v106, v107
	global_store_dwordx4 v[122:123], v[98:101], off offset:256
	s_and_saveexec_b64 s[28:29], s[8:9]
	v_readlane_b32 s62, v254, 61
	v_readlane_b32 s66, v254, 63
	v_readlane_b32 s38, v254, 59
	v_readlane_b32 s63, v254, 62
	v_readlane_b32 s67, v255, 0
	v_readlane_b32 s39, v254, 60
	s_cbranch_execz .LBB0_573
	s_waitcnt lgkmcnt(0)
	v_add_f32_e32 v96, v96, v97
	v_fma_f32 v96, v96, s65, 0.5
	v_trunc_f32_e32 v96, v96
	v_mul_f32_e32 v97, 0x2f800000, v96
	v_floor_f32_e32 v97, v97
	v_fmac_f32_e32 v96, 0xcf800000, v97
	v_cvt_u32_f32_e32 v96, v96
	v_cvt_u32_f32_e32 v97, v97
	global_atomic_add_x2 v[112:113], v[96:97], off offset:128
.LBB0_573:
	s_or_b64 exec, exec, s[28:29]
	v_or_b32_e32 v96, 32, v142
	s_waitcnt lgkmcnt(0)
	v_ashrrev_i32_e32 v97, 31, v96
	v_lshlrev_b64 v[96:97], 10, v[96:97]
	v_lshl_add_u64 v[104:105], v[96:97], 0, v[140:141]
	v_lshlrev_b64 v[106:107], 2, v[104:105]
	v_lshl_add_u64 v[108:109], s[16:17], 0, v[106:107]
	s_mov_b64 s[98:99], 0x80000
	v_lshl_add_u64 v[250:251], v[248:249], 0, s[98:99]
	global_load_dwordx4 v[216:219], v[250:251], off
	global_load_dwordx4 v[220:223], v[250:251], off offset:16
	global_load_dwordx4 v[224:227], v[250:251], off offset:512
	global_load_dwordx4 v[228:231], v[250:251], off offset:528
	s_waitcnt vmcnt(16)
	v_lshl_add_u64 v[104:105], v[104:105], 1, s[18:19]
	v_lshl_add_u64 v[106:107], s[12:13], 0, v[106:107]
	v_pk_add_f32 v[94:95], v[94:95], v[234:235]
	v_pk_add_f32 v[92:93], v[92:93], v[232:233]
	v_pk_add_f32 v[90:91], v[90:91], v[238:239]
	v_pk_add_f32 v[88:89], v[88:89], v[236:237]
	v_cvt_pk_bf16_f32 v96, v92, v93
	v_cvt_pk_bf16_f32 v97, v94, v95
	v_cvt_pk_bf16_f32 v98, v88, v89
	v_cvt_pk_bf16_f32 v99, v90, v91
	global_store_dwordx4 v[106:107], v[92:95], off
	global_store_dwordx4 v[106:107], v[88:91], off offset:16
	global_store_dwordx4 v[104:105], v[96:99], off
	s_nop 0
	v_mul_f32_e32 v93, v93, v93
	v_mul_f32_e32 v95, v95, v95
	v_mul_f32_e32 v89, v89, v89
	v_fmac_f32_e32 v93, v92, v92
	v_fmac_f32_e32 v95, v94, v94
	v_mul_f32_e32 v91, v91, v91
	v_fmac_f32_e32 v89, v88, v88
	v_add_f32_e32 v88, v93, v95
	v_fmac_f32_e32 v91, v90, v90
	v_add_f32_e32 v88, v88, v89
	v_add_f32_e32 v92, v91, v88
	v_pk_add_f32 v[86:87], v[86:87], v[242:243]
	v_pk_add_f32 v[84:85], v[84:85], v[240:241]
	v_pk_add_f32 v[90:91], v[82:83], v[246:247]
	v_pk_add_f32 v[88:89], v[80:81], v[244:245]
	v_mul_f32_e32 v81, v85, v85
	v_mul_f32_e32 v82, v87, v87
	v_mul_f32_e32 v83, v89, v89
	v_fmac_f32_e32 v81, v84, v84
	v_fmac_f32_e32 v82, v86, v86
	v_mul_f32_e32 v80, v91, v91
	v_add_f32_e32 v81, v81, v82
	v_fmac_f32_e32 v83, v88, v88
	v_fmac_f32_e32 v80, v90, v90
	v_add_f32_e32 v81, v81, v83
	v_add_f32_e32 v80, v80, v81
	v_add_f32_e32 v80, v92, v80
	ds_bpermute_b32 v81, v180, v80
	global_store_dwordx4 v[106:107], v[84:87], off offset:512
	global_store_dwordx4 v[106:107], v[88:91], off offset:528
	v_cvt_pk_bf16_f32 v82, v84, v85
	v_cvt_pk_bf16_f32 v83, v86, v87
	v_cvt_pk_bf16_f32 v84, v88, v89
	s_waitcnt lgkmcnt(0)
	v_add_f32_e32 v80, v80, v81
	ds_bpermute_b32 v81, v181, v80
	v_cvt_pk_bf16_f32 v85, v90, v91
	global_store_dwordx4 v[104:105], v[82:85], off offset:256
	s_and_saveexec_b64 s[28:29], s[8:9]
	s_cbranch_execz .LBB0_575
	s_waitcnt lgkmcnt(0)
	v_add_f32_e32 v80, v80, v81
	v_fma_f32 v80, v80, s65, 0.5
	v_trunc_f32_e32 v80, v80
	v_mul_f32_e32 v81, 0x2f800000, v80
	v_floor_f32_e32 v81, v81
	v_fmac_f32_e32 v80, 0xcf800000, v81
	v_cvt_u32_f32_e32 v80, v80
	v_cvt_u32_f32_e32 v81, v81
	global_atomic_add_x2 v[112:113], v[80:81], off offset:256
.LBB0_575:
	s_or_b64 exec, exec, s[28:29]
	v_or_b32_e32 v80, 48, v142
	s_waitcnt lgkmcnt(0)
	v_ashrrev_i32_e32 v81, 31, v80
	v_lshlrev_b64 v[80:81], 10, v[80:81]
	v_lshl_add_u64 v[88:89], v[80:81], 0, v[140:141]
	v_lshlrev_b64 v[90:91], 2, v[88:89]
	v_lshl_add_u64 v[92:93], s[16:17], 0, v[90:91]
	s_mov_b64 s[98:99], 0x90000
	v_lshl_add_u64 v[250:251], v[248:249], 0, s[98:99]
	global_load_dwordx4 v[232:235], v[250:251], off
	global_load_dwordx4 v[236:239], v[250:251], off offset:16
	global_load_dwordx4 v[240:243], v[250:251], off offset:512
	global_load_dwordx4 v[244:247], v[250:251], off offset:528
	s_waitcnt vmcnt(16)
	v_lshl_add_u64 v[88:89], v[88:89], 1, s[18:19]
	v_lshl_add_u64 v[90:91], s[12:13], 0, v[90:91]
	v_pk_add_f32 v[78:79], v[78:79], v[202:203]
	v_pk_add_f32 v[76:77], v[76:77], v[200:201]
	v_pk_add_f32 v[74:75], v[74:75], v[206:207]
	v_pk_add_f32 v[72:73], v[72:73], v[204:205]
	v_cvt_pk_bf16_f32 v80, v76, v77
	v_cvt_pk_bf16_f32 v81, v78, v79
	v_cvt_pk_bf16_f32 v82, v72, v73
	v_cvt_pk_bf16_f32 v83, v74, v75
	global_store_dwordx4 v[90:91], v[76:79], off
	global_store_dwordx4 v[90:91], v[72:75], off offset:16
	global_store_dwordx4 v[88:89], v[80:83], off
	s_nop 0
	v_mul_f32_e32 v77, v77, v77
	v_mul_f32_e32 v79, v79, v79
	v_mul_f32_e32 v73, v73, v73
	v_fmac_f32_e32 v77, v76, v76
	v_fmac_f32_e32 v79, v78, v78
	v_mul_f32_e32 v75, v75, v75
	v_fmac_f32_e32 v73, v72, v72
	v_add_f32_e32 v72, v77, v79
	v_fmac_f32_e32 v75, v74, v74
	v_add_f32_e32 v72, v72, v73
	v_add_f32_e32 v76, v75, v72
	v_pk_add_f32 v[70:71], v[70:71], v[210:211]
	v_pk_add_f32 v[68:69], v[68:69], v[208:209]
	v_pk_add_f32 v[74:75], v[66:67], v[214:215]
	v_pk_add_f32 v[72:73], v[64:65], v[212:213]
	v_mul_f32_e32 v65, v69, v69
	v_mul_f32_e32 v66, v71, v71
	v_mul_f32_e32 v67, v73, v73
	v_fmac_f32_e32 v65, v68, v68
	v_fmac_f32_e32 v66, v70, v70
	v_mul_f32_e32 v64, v75, v75
	v_add_f32_e32 v65, v65, v66
	v_fmac_f32_e32 v67, v72, v72
	v_fmac_f32_e32 v64, v74, v74
	v_add_f32_e32 v65, v65, v67
	v_add_f32_e32 v64, v64, v65
	v_add_f32_e32 v64, v76, v64
	ds_bpermute_b32 v65, v180, v64
	global_store_dwordx4 v[90:91], v[68:71], off offset:512
	global_store_dwordx4 v[90:91], v[72:75], off offset:528
	v_cvt_pk_bf16_f32 v66, v68, v69
	v_cvt_pk_bf16_f32 v67, v70, v71
	v_cvt_pk_bf16_f32 v68, v72, v73
	s_waitcnt lgkmcnt(0)
	v_add_f32_e32 v64, v64, v65
	ds_bpermute_b32 v65, v181, v64
	v_cvt_pk_bf16_f32 v69, v74, v75
	global_store_dwordx4 v[88:89], v[66:69], off offset:256
	s_and_saveexec_b64 s[28:29], s[8:9]
	s_cbranch_execz .LBB0_577
	s_waitcnt lgkmcnt(0)
	v_add_f32_e32 v64, v64, v65
	v_fma_f32 v64, v64, s65, 0.5
	v_trunc_f32_e32 v64, v64
	v_mul_f32_e32 v65, 0x2f800000, v64
	v_floor_f32_e32 v65, v65
	v_fmac_f32_e32 v64, 0xcf800000, v65
	v_cvt_u32_f32_e32 v64, v64
	v_cvt_u32_f32_e32 v65, v65
	global_atomic_add_x2 v[112:113], v[64:65], off offset:384
.LBB0_577:
	s_or_b64 exec, exec, s[28:29]
	s_mov_b64 s[28:29], 0x20000
	v_lshl_add_u64 v[72:73], v[138:139], 0, s[28:29]
	v_lshlrev_b64 v[74:75], 2, v[72:73]
	v_lshl_add_u64 v[76:77], s[16:17], 0, v[74:75]
	s_waitcnt lgkmcnt(0)
	s_mov_b64 s[98:99], 0xa0000
	v_lshl_add_u64 v[250:251], v[248:249], 0, s[98:99]
	global_load_dwordx4 v[200:203], v[250:251], off
	global_load_dwordx4 v[204:207], v[250:251], off offset:16
	global_load_dwordx4 v[208:211], v[250:251], off offset:512
	global_load_dwordx4 v[212:215], v[250:251], off offset:528
	s_waitcnt vmcnt(16)
	v_lshl_add_u64 v[72:73], v[72:73], 1, s[18:19]
	v_lshl_add_u64 v[74:75], s[12:13], 0, v[74:75]
	v_pk_add_f32 v[62:63], v[62:63], v[218:219]
	v_pk_add_f32 v[60:61], v[60:61], v[216:217]
	v_pk_add_f32 v[58:59], v[58:59], v[222:223]
	v_pk_add_f32 v[56:57], v[56:57], v[220:221]
	v_cvt_pk_bf16_f32 v64, v60, v61
	v_cvt_pk_bf16_f32 v65, v62, v63
	v_cvt_pk_bf16_f32 v66, v56, v57
	v_cvt_pk_bf16_f32 v67, v58, v59
	global_store_dwordx4 v[74:75], v[60:63], off
	global_store_dwordx4 v[74:75], v[56:59], off offset:16
	global_store_dwordx4 v[72:73], v[64:67], off
	s_nop 0
	v_mul_f32_e32 v61, v61, v61
	v_mul_f32_e32 v63, v63, v63
	v_mul_f32_e32 v57, v57, v57
	v_fmac_f32_e32 v61, v60, v60
	v_fmac_f32_e32 v63, v62, v62
	v_mul_f32_e32 v59, v59, v59
	v_fmac_f32_e32 v57, v56, v56
	v_add_f32_e32 v56, v61, v63
	v_fmac_f32_e32 v59, v58, v58
	v_add_f32_e32 v56, v56, v57
	v_add_f32_e32 v60, v59, v56
	v_pk_add_f32 v[54:55], v[54:55], v[226:227]
	v_pk_add_f32 v[52:53], v[52:53], v[224:225]
	v_pk_add_f32 v[58:59], v[50:51], v[230:231]
	v_pk_add_f32 v[56:57], v[48:49], v[228:229]
	v_mul_f32_e32 v49, v53, v53
	v_mul_f32_e32 v50, v55, v55
	v_mul_f32_e32 v51, v57, v57
	v_fmac_f32_e32 v49, v52, v52
	v_fmac_f32_e32 v50, v54, v54
	v_mul_f32_e32 v48, v59, v59
	v_add_f32_e32 v49, v49, v50
	v_fmac_f32_e32 v51, v56, v56
	v_fmac_f32_e32 v48, v58, v58
	v_add_f32_e32 v49, v49, v51
	v_add_f32_e32 v48, v48, v49
	v_add_f32_e32 v48, v60, v48
	ds_bpermute_b32 v49, v180, v48
	global_store_dwordx4 v[74:75], v[52:55], off offset:512
	global_store_dwordx4 v[74:75], v[56:59], off offset:528
	v_cvt_pk_bf16_f32 v50, v52, v53
	v_cvt_pk_bf16_f32 v51, v54, v55
	v_cvt_pk_bf16_f32 v52, v56, v57
	s_waitcnt lgkmcnt(0)
	v_add_f32_e32 v48, v48, v49
	ds_bpermute_b32 v49, v181, v48
	v_cvt_pk_bf16_f32 v53, v58, v59
	global_store_dwordx4 v[72:73], v[50:53], off offset:256
	s_and_saveexec_b64 s[28:29], s[8:9]
	s_cbranch_execz .LBB0_579
	s_waitcnt lgkmcnt(0)
	v_add_f32_e32 v48, v48, v49
	v_fma_f32 v48, v48, s65, 0.5
	v_trunc_f32_e32 v48, v48
	v_mul_f32_e32 v49, 0x2f800000, v48
	v_floor_f32_e32 v49, v49
	v_fmac_f32_e32 v48, 0xcf800000, v49
	v_cvt_u32_f32_e32 v48, v48
	v_cvt_u32_f32_e32 v49, v49
	global_atomic_add_x2 v[112:113], v[48:49], off offset:1024
.LBB0_579:
	s_or_b64 exec, exec, s[28:29]
	s_mov_b64 s[28:29], 0x24000
	v_lshl_add_u64 v[56:57], v[138:139], 0, s[28:29]
	v_lshlrev_b64 v[58:59], 2, v[56:57]
	v_lshl_add_u64 v[60:61], s[16:17], 0, v[58:59]
	s_waitcnt lgkmcnt(0)
	s_mov_b64 s[98:99], 0xb0000
	v_lshl_add_u64 v[250:251], v[248:249], 0, s[98:99]
	global_load_dwordx4 v[216:219], v[250:251], off
	global_load_dwordx4 v[220:223], v[250:251], off offset:16
	global_load_dwordx4 v[224:227], v[250:251], off offset:512
	global_load_dwordx4 v[228:231], v[250:251], off offset:528
	s_waitcnt vmcnt(16)
	v_lshl_add_u64 v[56:57], v[56:57], 1, s[18:19]
	v_lshl_add_u64 v[58:59], s[12:13], 0, v[58:59]
	v_pk_add_f32 v[46:47], v[46:47], v[234:235]
	v_pk_add_f32 v[44:45], v[44:45], v[232:233]
	v_pk_add_f32 v[42:43], v[42:43], v[238:239]
	v_pk_add_f32 v[40:41], v[40:41], v[236:237]
	v_cvt_pk_bf16_f32 v48, v44, v45
	v_cvt_pk_bf16_f32 v49, v46, v47
	v_cvt_pk_bf16_f32 v50, v40, v41
	v_cvt_pk_bf16_f32 v51, v42, v43
	global_store_dwordx4 v[58:59], v[44:47], off
	global_store_dwordx4 v[58:59], v[40:43], off offset:16
	global_store_dwordx4 v[56:57], v[48:51], off
	s_nop 0
	v_mul_f32_e32 v45, v45, v45
	v_mul_f32_e32 v47, v47, v47
	v_mul_f32_e32 v41, v41, v41
	v_fmac_f32_e32 v45, v44, v44
	v_fmac_f32_e32 v47, v46, v46
	v_mul_f32_e32 v43, v43, v43
	v_fmac_f32_e32 v41, v40, v40
	v_add_f32_e32 v40, v45, v47
	v_fmac_f32_e32 v43, v42, v42
	v_add_f32_e32 v40, v40, v41
	v_add_f32_e32 v44, v43, v40
	v_pk_add_f32 v[38:39], v[38:39], v[242:243]
	v_pk_add_f32 v[36:37], v[36:37], v[240:241]
	v_pk_add_f32 v[42:43], v[34:35], v[246:247]
	v_pk_add_f32 v[40:41], v[32:33], v[244:245]
	v_mul_f32_e32 v33, v37, v37
	v_mul_f32_e32 v34, v39, v39
	v_mul_f32_e32 v35, v41, v41
	v_fmac_f32_e32 v33, v36, v36
	v_fmac_f32_e32 v34, v38, v38
	v_mul_f32_e32 v32, v43, v43
	v_add_f32_e32 v33, v33, v34
	v_fmac_f32_e32 v35, v40, v40
	v_fmac_f32_e32 v32, v42, v42
	v_add_f32_e32 v33, v33, v35
	v_add_f32_e32 v32, v32, v33
	v_add_f32_e32 v32, v44, v32
	ds_bpermute_b32 v33, v180, v32
	global_store_dwordx4 v[58:59], v[36:39], off offset:512
	global_store_dwordx4 v[58:59], v[40:43], off offset:528
	v_cvt_pk_bf16_f32 v34, v36, v37
	v_cvt_pk_bf16_f32 v35, v38, v39
	v_cvt_pk_bf16_f32 v36, v40, v41
	s_waitcnt lgkmcnt(0)
	v_add_f32_e32 v32, v32, v33
	ds_bpermute_b32 v33, v181, v32
	v_cvt_pk_bf16_f32 v37, v42, v43
	global_store_dwordx4 v[56:57], v[34:37], off offset:256
	s_and_saveexec_b64 s[28:29], s[8:9]
	s_cbranch_execz .LBB0_581
	s_waitcnt lgkmcnt(0)
	v_add_f32_e32 v32, v32, v33
	v_fma_f32 v32, v32, s65, 0.5
	v_trunc_f32_e32 v32, v32
	v_mul_f32_e32 v33, 0x2f800000, v32
	v_floor_f32_e32 v33, v33
	v_fmac_f32_e32 v32, 0xcf800000, v33
	v_cvt_u32_f32_e32 v32, v32
	v_cvt_u32_f32_e32 v33, v33
	global_atomic_add_x2 v[112:113], v[32:33], off offset:1152
.LBB0_581:
	s_or_b64 exec, exec, s[28:29]
	s_mov_b64 s[28:29], 0x28000
	v_lshl_add_u64 v[40:41], v[138:139], 0, s[28:29]
	v_lshlrev_b64 v[42:43], 2, v[40:41]
	v_lshl_add_u64 v[44:45], s[16:17], 0, v[42:43]
	s_waitcnt lgkmcnt(0)
	s_waitcnt vmcnt(12)
	v_lshl_add_u64 v[40:41], v[40:41], 1, s[18:19]
	v_lshl_add_u64 v[42:43], s[12:13], 0, v[42:43]
	v_pk_add_f32 v[30:31], v[30:31], v[202:203]
	v_pk_add_f32 v[28:29], v[28:29], v[200:201]
	v_pk_add_f32 v[26:27], v[26:27], v[206:207]
	v_pk_add_f32 v[24:25], v[24:25], v[204:205]
	v_cvt_pk_bf16_f32 v32, v28, v29
	v_cvt_pk_bf16_f32 v33, v30, v31
	v_cvt_pk_bf16_f32 v34, v24, v25
	v_cvt_pk_bf16_f32 v35, v26, v27
	global_store_dwordx4 v[42:43], v[28:31], off
	global_store_dwordx4 v[42:43], v[24:27], off offset:16
	global_store_dwordx4 v[40:41], v[32:35], off
	s_nop 0
	v_mul_f32_e32 v29, v29, v29
	v_mul_f32_e32 v31, v31, v31
	v_mul_f32_e32 v25, v25, v25
	v_fmac_f32_e32 v29, v28, v28
	v_fmac_f32_e32 v31, v30, v30
	v_mul_f32_e32 v27, v27, v27
	v_fmac_f32_e32 v25, v24, v24
	v_add_f32_e32 v24, v29, v31
	v_fmac_f32_e32 v27, v26, v26
	v_add_f32_e32 v24, v24, v25
	v_add_f32_e32 v28, v27, v24
	v_pk_add_f32 v[22:23], v[22:23], v[210:211]
	v_pk_add_f32 v[20:21], v[20:21], v[208:209]
	v_pk_add_f32 v[26:27], v[18:19], v[214:215]
	v_pk_add_f32 v[24:25], v[16:17], v[212:213]
	v_mul_f32_e32 v17, v21, v21
	v_mul_f32_e32 v18, v23, v23
	v_mul_f32_e32 v19, v25, v25
	v_fmac_f32_e32 v17, v20, v20
	v_fmac_f32_e32 v18, v22, v22
	v_mul_f32_e32 v16, v27, v27
	v_add_f32_e32 v17, v17, v18
	v_fmac_f32_e32 v19, v24, v24
	v_fmac_f32_e32 v16, v26, v26
	v_add_f32_e32 v17, v17, v19
	v_add_f32_e32 v16, v16, v17
	v_add_f32_e32 v16, v28, v16
	ds_bpermute_b32 v17, v180, v16
	global_store_dwordx4 v[42:43], v[20:23], off offset:512
	global_store_dwordx4 v[42:43], v[24:27], off offset:528
	v_cvt_pk_bf16_f32 v18, v20, v21
	v_cvt_pk_bf16_f32 v19, v22, v23
	v_cvt_pk_bf16_f32 v20, v24, v25
	s_waitcnt lgkmcnt(0)
	v_add_f32_e32 v16, v16, v17
	ds_bpermute_b32 v17, v181, v16
	v_cvt_pk_bf16_f32 v21, v26, v27
	global_store_dwordx4 v[40:41], v[18:21], off offset:256
	s_and_saveexec_b64 s[28:29], s[8:9]
	s_cbranch_execz .LBB0_583
	s_waitcnt lgkmcnt(0)
	v_add_f32_e32 v16, v16, v17
	v_fma_f32 v16, v16, s65, 0.5
	v_trunc_f32_e32 v16, v16
	v_mul_f32_e32 v17, 0x2f800000, v16
	v_floor_f32_e32 v17, v17
	v_fmac_f32_e32 v16, 0xcf800000, v17
	v_cvt_u32_f32_e32 v16, v16
	v_cvt_u32_f32_e32 v17, v17
	global_atomic_add_x2 v[112:113], v[16:17], off offset:1280
.LBB0_583:
	s_or_b64 exec, exec, s[28:29]
	s_mov_b64 s[28:29], 0x2c000
	v_lshl_add_u64 v[24:25], v[138:139], 0, s[28:29]
	v_lshlrev_b64 v[26:27], 2, v[24:25]
	v_lshl_add_u64 v[28:29], s[16:17], 0, v[26:27]
	s_waitcnt lgkmcnt(0)
	s_waitcnt vmcnt(8)
	v_lshl_add_u64 v[24:25], v[24:25], 1, s[18:19]
	v_lshl_add_u64 v[26:27], s[12:13], 0, v[26:27]
	v_pk_add_f32 v[14:15], v[14:15], v[218:219]
	v_pk_add_f32 v[12:13], v[12:13], v[216:217]
	v_pk_add_f32 v[10:11], v[10:11], v[222:223]
	v_pk_add_f32 v[8:9], v[8:9], v[220:221]
	v_cvt_pk_bf16_f32 v16, v12, v13
	v_cvt_pk_bf16_f32 v17, v14, v15
	v_cvt_pk_bf16_f32 v18, v8, v9
	v_cvt_pk_bf16_f32 v19, v10, v11
	global_store_dwordx4 v[26:27], v[12:15], off
	global_store_dwordx4 v[26:27], v[8:11], off offset:16
	global_store_dwordx4 v[24:25], v[16:19], off
	s_nop 0
	v_mul_f32_e32 v13, v13, v13
	v_mul_f32_e32 v15, v15, v15
	v_mul_f32_e32 v9, v9, v9
	v_fmac_f32_e32 v13, v12, v12
	v_fmac_f32_e32 v15, v14, v14
	v_mul_f32_e32 v11, v11, v11
	v_fmac_f32_e32 v9, v8, v8
	v_add_f32_e32 v8, v13, v15
	v_fmac_f32_e32 v11, v10, v10
	v_add_f32_e32 v8, v8, v9
	v_add_f32_e32 v12, v11, v8
	v_pk_add_f32 v[6:7], v[6:7], v[226:227]
	v_pk_add_f32 v[4:5], v[4:5], v[224:225]
	v_pk_add_f32 v[10:11], v[2:3], v[230:231]
	v_pk_add_f32 v[8:9], v[0:1], v[228:229]
	v_mul_f32_e32 v1, v5, v5
	v_mul_f32_e32 v2, v7, v7
	v_mul_f32_e32 v3, v9, v9
	v_fmac_f32_e32 v1, v4, v4
	v_fmac_f32_e32 v2, v6, v6
	v_mul_f32_e32 v0, v11, v11
	v_add_f32_e32 v1, v1, v2
	v_fmac_f32_e32 v3, v8, v8
	v_fmac_f32_e32 v0, v10, v10
	v_add_f32_e32 v1, v1, v3
	v_add_f32_e32 v0, v0, v1
	v_add_f32_e32 v0, v12, v0
	ds_bpermute_b32 v1, v180, v0
	global_store_dwordx4 v[26:27], v[4:7], off offset:512
	global_store_dwordx4 v[26:27], v[8:11], off offset:528
	v_cvt_pk_bf16_f32 v2, v4, v5
	v_cvt_pk_bf16_f32 v3, v6, v7
	v_cvt_pk_bf16_f32 v4, v8, v9
	s_waitcnt lgkmcnt(0)
	v_add_f32_e32 v0, v0, v1
	ds_bpermute_b32 v1, v181, v0
	v_cvt_pk_bf16_f32 v5, v10, v11
	global_store_dwordx4 v[24:25], v[2:5], off offset:256
	s_and_saveexec_b64 s[28:29], s[8:9]
	s_cbranch_execz .LBB0_560
	s_waitcnt lgkmcnt(0)
	v_add_f32_e32 v0, v0, v1
	v_fma_f32 v0, v0, s65, 0.5
	v_trunc_f32_e32 v0, v0
	v_mul_f32_e32 v1, 0x2f800000, v0
	v_floor_f32_e32 v1, v1
	v_fmac_f32_e32 v0, 0xcf800000, v1
	v_cvt_u32_f32_e32 v0, v0
	v_cvt_u32_f32_e32 v1, v1
	global_atomic_add_x2 v[112:113], v[0:1], off offset:1408
	s_branch .LBB0_560

.LBB0_725:
	s_add_u32 s26, s24, 0xfff00080
	s_addc_u32 s27, s25, -1
	s_add_i32 s63, s44, 0x120
	s_cmp_eq_u32 s62, 60
	s_cselect_b32 s29, s19, s27
	s_cselect_b32 s28, s58, s26
	s_cselect_b32 s27, s17, s61
	s_cselect_b32 s26, s59, s60
	s_add_i32 s68, s45, 0x120
	v_add_u32_e32 v154, s63, v147
	v_add_u32_e32 v158, s68, v147
	ds_read_b128 v[138:141], v154
	ds_read_b128 v[142:145], v154 offset:1024
	ds_read_b128 v[150:153], v154 offset:2048
	ds_read_b128 v[154:157], v154 offset:3072
	ds_read_b128 v[200:203], v158
	ds_read_b128 v[204:207], v158 offset:1024
	ds_read_b128 v[208:211], v158 offset:2048
	ds_read_b128 v[212:215], v158 offset:3072
	v_lshl_add_u64 v[158:159], s[24:25], 0, v[134:135]
	s_add_i32 m0, s43, 0xc000
	ds_read_b128 v[216:219], v149
	ds_read_b128 v[220:223], v149 offset:1024
	ds_read_b128 v[224:227], v149 offset:2048
	ds_read_b128 v[228:231], v149 offset:3072
	ds_read_b128 v[232:235], v149 offset:4096
	ds_read_b128 v[236:239], v149 offset:5120
	ds_read_b128 v[240:243], v149 offset:6144
	ds_read_b128 v[244:247], v149 offset:7168
	global_load_lds_dwordx4 v[158:159], off
	v_lshl_add_u64 v[158:159], s[24:25], 0, v[136:137]
	s_add_i32 m0, s43, 0xe000
	s_nop 0
	global_load_lds_dwordx4 v[158:159], off
	s_waitcnt vmcnt(8)
	s_waitcnt lgkmcnt(0)
	s_barrier
	s_setprio 1
	s_waitcnt lgkmcnt(0)
	v_mfma_f32_16x16x32_bf16 v[124:127], v[138:141], v[216:219], v[124:127]
	v_mfma_f32_16x16x32_bf16 v[120:123], v[150:153], v[216:219], v[120:123]
	v_mfma_f32_16x16x32_bf16 v[108:111], v[138:141], v[224:227], v[108:111]
	v_mfma_f32_16x16x32_bf16 v[104:107], v[150:153], v[224:227], v[104:107]
	v_mfma_f32_16x16x32_bf16 v[92:95], v[138:141], v[232:235], v[92:95]
	v_mfma_f32_16x16x32_bf16 v[88:91], v[150:153], v[232:235], v[88:91]
	v_mfma_f32_16x16x32_bf16 v[76:79], v[138:141], v[240:243], v[76:79]
	v_mfma_f32_16x16x32_bf16 v[72:75], v[150:153], v[240:243], v[72:75]
	v_mfma_f32_16x16x32_bf16 v[124:127], v[142:145], v[220:223], v[124:127]
	v_mfma_f32_16x16x32_bf16 v[120:123], v[154:157], v[220:223], v[120:123]
	v_mfma_f32_16x16x32_bf16 v[108:111], v[142:145], v[228:231], v[108:111]
	v_mfma_f32_16x16x32_bf16 v[104:107], v[154:157], v[228:231], v[104:107]
	v_mfma_f32_16x16x32_bf16 v[92:95], v[142:145], v[236:239], v[92:95]
	v_mfma_f32_16x16x32_bf16 v[88:91], v[154:157], v[236:239], v[88:91]
	v_mfma_f32_16x16x32_bf16 v[76:79], v[142:145], v[244:247], v[76:79]
	v_mfma_f32_16x16x32_bf16 v[72:75], v[154:157], v[244:247], v[72:75]
	s_setprio 0
	s_setprio 1
	v_mfma_f32_16x16x32_bf16 v[116:119], v[200:203], v[216:219], v[116:119]
	v_mfma_f32_16x16x32_bf16 v[112:115], v[208:211], v[216:219], v[112:115]
	v_mfma_f32_16x16x32_bf16 v[100:103], v[200:203], v[224:227], v[100:103]
	v_mfma_f32_16x16x32_bf16 v[96:99], v[208:211], v[224:227], v[96:99]
	v_mfma_f32_16x16x32_bf16 v[84:87], v[200:203], v[232:235], v[84:87]
	v_mfma_f32_16x16x32_bf16 v[80:83], v[208:211], v[232:235], v[80:83]
	v_mfma_f32_16x16x32_bf16 v[68:71], v[200:203], v[240:243], v[68:71]
	v_mfma_f32_16x16x32_bf16 v[64:67], v[208:211], v[240:243], v[64:67]
	v_mfma_f32_16x16x32_bf16 v[116:119], v[204:207], v[220:223], v[116:119]
	v_mfma_f32_16x16x32_bf16 v[112:115], v[212:215], v[220:223], v[112:115]
	v_mfma_f32_16x16x32_bf16 v[100:103], v[204:207], v[228:231], v[100:103]
	v_mfma_f32_16x16x32_bf16 v[96:99], v[212:215], v[228:231], v[96:99]
	v_mfma_f32_16x16x32_bf16 v[84:87], v[204:207], v[236:239], v[84:87]
	v_mfma_f32_16x16x32_bf16 v[80:83], v[212:215], v[236:239], v[80:83]
	v_mfma_f32_16x16x32_bf16 v[68:71], v[204:207], v[244:247], v[68:71]
	v_mfma_f32_16x16x32_bf16 v[64:67], v[212:215], v[244:247], v[64:67]
	s_setprio 0
	s_barrier
	s_add_i32 s63, s63, s42
	v_lshl_add_u64 v[158:159], s[26:27], 0, v[160:161]
	s_mov_b32 m0, s63
	ds_read_b128 v[216:219], v149 offset:16384
	ds_read_b128 v[220:223], v149 offset:17408
	ds_read_b128 v[224:227], v149 offset:18432
	ds_read_b128 v[228:231], v149 offset:19456
	ds_read_b128 v[232:235], v149 offset:20480
	ds_read_b128 v[236:239], v149 offset:21504
	ds_read_b128 v[240:243], v149 offset:22528
	ds_read_b128 v[244:247], v149 offset:23552
	global_load_lds_dwordx4 v[158:159], off
	s_add_i32 m0, s63, 0x2000
	s_add_u32 s66, s26, 0x100000
	v_lshl_add_u64 v[170:171], s[26:27], 0, v[128:129]
	s_addc_u32 s67, s27, 0
	s_add_i32 s63, s68, s42
	global_load_lds_dwordx4 v[170:171], off
	v_lshl_add_u64 v[174:175], s[66:67], 0, v[160:161]
	s_mov_b32 m0, s63
	v_lshl_add_u64 v[198:199], s[28:29], 0, v[130:131]
	global_load_lds_dwordx4 v[174:175], off
	v_lshl_add_u64 v[174:175], s[66:67], 0, v[128:129]
	s_add_i32 m0, s63, 0x2000
	s_nop 0
	global_load_lds_dwordx4 v[174:175], off
	v_lshl_add_u64 v[174:175], s[28:29], 0, v[132:133]
	s_mov_b32 m0, s43
	s_nop 0
	global_load_lds_dwordx4 v[174:175], off
	s_mov_b32 m0, s48
	s_nop 0
	global_load_lds_dwordx4 v[198:199], off
	s_waitcnt vmcnt(8)
	s_waitcnt lgkmcnt(0)
	s_barrier
	s_setprio 1
	s_waitcnt lgkmcnt(0)
	v_mfma_f32_16x16x32_bf16 v[60:63], v[138:141], v[216:219], v[60:63]
	v_mfma_f32_16x16x32_bf16 v[56:59], v[150:153], v[216:219], v[56:59]
	v_mfma_f32_16x16x32_bf16 v[44:47], v[138:141], v[224:227], v[44:47]
	v_mfma_f32_16x16x32_bf16 v[40:43], v[150:153], v[224:227], v[40:43]
	v_mfma_f32_16x16x32_bf16 v[28:31], v[138:141], v[232:235], v[28:31]
	v_mfma_f32_16x16x32_bf16 v[24:27], v[150:153], v[232:235], v[24:27]
	v_mfma_f32_16x16x32_bf16 v[12:15], v[138:141], v[240:243], v[12:15]
	v_mfma_f32_16x16x32_bf16 v[8:11], v[150:153], v[240:243], v[8:11]
	v_mfma_f32_16x16x32_bf16 v[60:63], v[142:145], v[220:223], v[60:63]
	v_mfma_f32_16x16x32_bf16 v[56:59], v[154:157], v[220:223], v[56:59]
	v_mfma_f32_16x16x32_bf16 v[44:47], v[142:145], v[228:231], v[44:47]
	v_mfma_f32_16x16x32_bf16 v[40:43], v[154:157], v[228:231], v[40:43]
	v_mfma_f32_16x16x32_bf16 v[28:31], v[142:145], v[236:239], v[28:31]
	v_mfma_f32_16x16x32_bf16 v[24:27], v[154:157], v[236:239], v[24:27]
	v_mfma_f32_16x16x32_bf16 v[12:15], v[142:145], v[244:247], v[12:15]
	v_mfma_f32_16x16x32_bf16 v[8:11], v[154:157], v[244:247], v[8:11]
	s_setprio 0
	s_setprio 1
	v_mfma_f32_16x16x32_bf16 v[52:55], v[200:203], v[216:219], v[52:55]
	v_mfma_f32_16x16x32_bf16 v[48:51], v[208:211], v[216:219], v[48:51]
	v_mfma_f32_16x16x32_bf16 v[36:39], v[200:203], v[224:227], v[36:39]
	v_mfma_f32_16x16x32_bf16 v[32:35], v[208:211], v[224:227], v[32:35]
	v_mfma_f32_16x16x32_bf16 v[20:23], v[200:203], v[232:235], v[20:23]
	v_mfma_f32_16x16x32_bf16 v[16:19], v[208:211], v[232:235], v[16:19]
	v_mfma_f32_16x16x32_bf16 v[4:7], v[200:203], v[240:243], v[4:7]
	v_mfma_f32_16x16x32_bf16 v[0:3], v[208:211], v[240:243], v[0:3]
	v_mfma_f32_16x16x32_bf16 v[52:55], v[204:207], v[220:223], v[52:55]
	v_mfma_f32_16x16x32_bf16 v[48:51], v[212:215], v[220:223], v[48:51]
	v_mfma_f32_16x16x32_bf16 v[36:39], v[204:207], v[228:231], v[36:39]
	v_mfma_f32_16x16x32_bf16 v[32:35], v[212:215], v[228:231], v[32:35]
	v_mfma_f32_16x16x32_bf16 v[20:23], v[204:207], v[236:239], v[20:23]
	v_mfma_f32_16x16x32_bf16 v[16:19], v[212:215], v[236:239], v[16:19]
	v_mfma_f32_16x16x32_bf16 v[4:7], v[204:207], v[244:247], v[4:7]
	v_mfma_f32_16x16x32_bf16 v[0:3], v[212:215], v[244:247], v[0:3]
	s_setprio 0
	s_barrier
	s_add_i32 s63, s46, 0x120
	s_add_i32 s66, s47, 0x120
	v_add_u32_e32 v154, s63, v147
	v_add_u32_e32 v172, s66, v147
	ds_read_b128 v[138:141], v154
	ds_read_b128 v[142:145], v154 offset:1024
	ds_read_b128 v[150:153], v154 offset:2048
	ds_read_b128 v[154:157], v154 offset:3072
	ds_read_b128 v[200:203], v172
	ds_read_b128 v[204:207], v172 offset:1024
	ds_read_b128 v[208:211], v172 offset:2048
	ds_read_b128 v[212:215], v172 offset:3072
	s_add_u32 s28, s28, 0x100000
	s_addc_u32 s29, s29, 0
	s_mov_b32 m0, s49
	v_lshl_add_u64 v[248:249], s[28:29], 0, v[132:133]
	ds_read_b128 v[216:219], v149 offset:32768
	ds_read_b128 v[220:223], v149 offset:33792
	ds_read_b128 v[224:227], v149 offset:34816
	ds_read_b128 v[228:231], v149 offset:35840
	ds_read_b128 v[232:235], v149 offset:36864
	ds_read_b128 v[236:239], v149 offset:37888
	ds_read_b128 v[240:243], v149 offset:38912
	ds_read_b128 v[244:247], v149 offset:39936
	global_load_lds_dwordx4 v[248:249], off
	v_lshl_add_u64 v[248:249], s[28:29], 0, v[130:131]
	s_mov_b32 m0, s52
	s_nop 0
	global_load_lds_dwordx4 v[248:249], off
	s_waitcnt vmcnt(8)
	s_waitcnt lgkmcnt(0)
	s_barrier
	s_setprio 1
	s_waitcnt lgkmcnt(0)
	v_mfma_f32_16x16x32_bf16 v[124:127], v[138:141], v[216:219], v[124:127]
	v_mfma_f32_16x16x32_bf16 v[120:123], v[150:153], v[216:219], v[120:123]
	v_mfma_f32_16x16x32_bf16 v[108:111], v[138:141], v[224:227], v[108:111]
	v_mfma_f32_16x16x32_bf16 v[104:107], v[150:153], v[224:227], v[104:107]
	v_mfma_f32_16x16x32_bf16 v[92:95], v[138:141], v[232:235], v[92:95]
	v_mfma_f32_16x16x32_bf16 v[88:91], v[150:153], v[232:235], v[88:91]
	v_mfma_f32_16x16x32_bf16 v[76:79], v[138:141], v[240:243], v[76:79]
	v_mfma_f32_16x16x32_bf16 v[72:75], v[150:153], v[240:243], v[72:75]
	v_mfma_f32_16x16x32_bf16 v[124:127], v[142:145], v[220:223], v[124:127]
	v_mfma_f32_16x16x32_bf16 v[120:123], v[154:157], v[220:223], v[120:123]
	v_mfma_f32_16x16x32_bf16 v[108:111], v[142:145], v[228:231], v[108:111]
	v_mfma_f32_16x16x32_bf16 v[104:107], v[154:157], v[228:231], v[104:107]
	v_mfma_f32_16x16x32_bf16 v[92:95], v[142:145], v[236:239], v[92:95]
	v_mfma_f32_16x16x32_bf16 v[88:91], v[154:157], v[236:239], v[88:91]
	v_mfma_f32_16x16x32_bf16 v[76:79], v[142:145], v[244:247], v[76:79]
	v_mfma_f32_16x16x32_bf16 v[72:75], v[154:157], v[244:247], v[72:75]
	s_setprio 0
	s_setprio 1
	v_mfma_f32_16x16x32_bf16 v[116:119], v[200:203], v[216:219], v[116:119]
	v_mfma_f32_16x16x32_bf16 v[112:115], v[208:211], v[216:219], v[112:115]
	v_mfma_f32_16x16x32_bf16 v[100:103], v[200:203], v[224:227], v[100:103]
	v_mfma_f32_16x16x32_bf16 v[96:99], v[208:211], v[224:227], v[96:99]
	v_mfma_f32_16x16x32_bf16 v[84:87], v[200:203], v[232:235], v[84:87]
	v_mfma_f32_16x16x32_bf16 v[80:83], v[208:211], v[232:235], v[80:83]
	v_mfma_f32_16x16x32_bf16 v[68:71], v[200:203], v[240:243], v[68:71]
	v_mfma_f32_16x16x32_bf16 v[64:67], v[208:211], v[240:243], v[64:67]
	v_mfma_f32_16x16x32_bf16 v[116:119], v[204:207], v[220:223], v[116:119]
	v_mfma_f32_16x16x32_bf16 v[112:115], v[212:215], v[220:223], v[112:115]
	v_mfma_f32_16x16x32_bf16 v[100:103], v[204:207], v[228:231], v[100:103]
	v_mfma_f32_16x16x32_bf16 v[96:99], v[212:215], v[228:231], v[96:99]
	v_mfma_f32_16x16x32_bf16 v[84:87], v[204:207], v[236:239], v[84:87]
	v_mfma_f32_16x16x32_bf16 v[80:83], v[212:215], v[236:239], v[80:83]
	v_mfma_f32_16x16x32_bf16 v[68:71], v[204:207], v[244:247], v[68:71]
	v_mfma_f32_16x16x32_bf16 v[64:67], v[212:215], v[244:247], v[64:67]
	s_setprio 0
	s_barrier
	s_add_i32 s28, s63, s42
	v_lshl_add_u64 v[158:159], v[158:159], 0, s[88:89]
	s_mov_b32 m0, s28
	ds_read_b128 v[216:219], v149 offset:49152
	ds_read_b128 v[220:223], v149 offset:50176
	ds_read_b128 v[224:227], v149 offset:51200
	ds_read_b128 v[228:231], v149 offset:52224
	ds_read_b128 v[232:235], v149 offset:53248
	ds_read_b128 v[236:239], v149 offset:54272
	ds_read_b128 v[240:243], v149 offset:55296
	ds_read_b128 v[244:247], v149 offset:56320
	global_load_lds_dwordx4 v[158:159], off
	s_add_i32 m0, s28, 0x2000
	s_add_u32 s26, s26, 0x100080
	v_lshl_add_u64 v[158:159], v[170:171], 0, s[88:89]
	s_addc_u32 s27, s27, 0
	s_add_i32 s28, s66, s42
	global_load_lds_dwordx4 v[158:159], off
	v_lshl_add_u64 v[158:159], s[26:27], 0, v[160:161]
	s_mov_b32 m0, s28
	s_nop 0
	global_load_lds_dwordx4 v[158:159], off
	v_lshl_add_u64 v[158:159], s[26:27], 0, v[128:129]
	s_add_i32 m0, s28, 0x2000
	s_nop 0
	global_load_lds_dwordx4 v[158:159], off
	v_lshl_add_u64 v[158:159], v[174:175], 0, s[88:89]
	s_mov_b32 m0, s53
	s_nop 0
	global_load_lds_dwordx4 v[158:159], off
	v_lshl_add_u64 v[158:159], v[198:199], 0, s[88:89]
	s_mov_b32 m0, s56
	s_nop 0
	global_load_lds_dwordx4 v[158:159], off
	s_waitcnt vmcnt(8)
	s_waitcnt lgkmcnt(0)
	s_barrier
	s_setprio 1
	s_waitcnt lgkmcnt(0)
	v_mfma_f32_16x16x32_bf16 v[60:63], v[138:141], v[216:219], v[60:63]
	v_mfma_f32_16x16x32_bf16 v[56:59], v[150:153], v[216:219], v[56:59]
	v_mfma_f32_16x16x32_bf16 v[44:47], v[138:141], v[224:227], v[44:47]
	v_mfma_f32_16x16x32_bf16 v[40:43], v[150:153], v[224:227], v[40:43]
	v_mfma_f32_16x16x32_bf16 v[28:31], v[138:141], v[232:235], v[28:31]
	v_mfma_f32_16x16x32_bf16 v[24:27], v[150:153], v[232:235], v[24:27]
	v_mfma_f32_16x16x32_bf16 v[12:15], v[138:141], v[240:243], v[12:15]
	v_mfma_f32_16x16x32_bf16 v[8:11], v[150:153], v[240:243], v[8:11]
	v_mfma_f32_16x16x32_bf16 v[60:63], v[142:145], v[220:223], v[60:63]
	v_mfma_f32_16x16x32_bf16 v[56:59], v[154:157], v[220:223], v[56:59]
	v_mfma_f32_16x16x32_bf16 v[44:47], v[142:145], v[228:231], v[44:47]
	v_mfma_f32_16x16x32_bf16 v[40:43], v[154:157], v[228:231], v[40:43]
	v_mfma_f32_16x16x32_bf16 v[28:31], v[142:145], v[236:239], v[28:31]
	v_mfma_f32_16x16x32_bf16 v[24:27], v[154:157], v[236:239], v[24:27]
	v_mfma_f32_16x16x32_bf16 v[12:15], v[142:145], v[244:247], v[12:15]
	v_mfma_f32_16x16x32_bf16 v[8:11], v[154:157], v[244:247], v[8:11]
	s_setprio 0
	s_setprio 1
	v_mfma_f32_16x16x32_bf16 v[52:55], v[200:203], v[216:219], v[52:55]
	v_mfma_f32_16x16x32_bf16 v[48:51], v[208:211], v[216:219], v[48:51]
	v_mfma_f32_16x16x32_bf16 v[36:39], v[200:203], v[224:227], v[36:39]
	v_mfma_f32_16x16x32_bf16 v[32:35], v[208:211], v[224:227], v[32:35]
	v_mfma_f32_16x16x32_bf16 v[20:23], v[200:203], v[232:235], v[20:23]
	v_mfma_f32_16x16x32_bf16 v[16:19], v[208:211], v[232:235], v[16:19]
	v_mfma_f32_16x16x32_bf16 v[4:7], v[200:203], v[240:243], v[4:7]
	v_mfma_f32_16x16x32_bf16 v[0:3], v[208:211], v[240:243], v[0:3]
	v_mfma_f32_16x16x32_bf16 v[52:55], v[204:207], v[220:223], v[52:55]
	v_mfma_f32_16x16x32_bf16 v[48:51], v[212:215], v[220:223], v[48:51]
	v_mfma_f32_16x16x32_bf16 v[36:39], v[204:207], v[228:231], v[36:39]
	v_mfma_f32_16x16x32_bf16 v[32:35], v[212:215], v[228:231], v[32:35]
	v_mfma_f32_16x16x32_bf16 v[20:23], v[204:207], v[236:239], v[20:23]
	v_mfma_f32_16x16x32_bf16 v[16:19], v[212:215], v[236:239], v[16:19]
	v_mfma_f32_16x16x32_bf16 v[4:7], v[204:207], v[244:247], v[4:7]
	v_mfma_f32_16x16x32_bf16 v[0:3], v[212:215], v[244:247], v[0:3]
	s_setprio 0
	s_barrier
	s_add_i32 s62, s62, 2
	s_add_u32 s24, s24, 0x100
	s_addc_u32 s25, s25, 0
	s_add_u32 s60, s60, 0x100
	s_addc_u32 s61, s61, 0
	s_cmp_gt_u32 s62, 61
	s_cbranch_scc0 .LBB0_725
	v_lshl_add_u32 v138, s51, 8, v146
	v_lshl_or_b32 v142, s1, 8, v148
	v_ashrrev_i32_e32 v139, 31, v138
	v_ashrrev_i32_e32 v143, 31, v142
	v_lshlrev_b64 v[140:141], 10, v[138:139]
	v_lshl_add_u64 v[140:141], v[140:141], 0, v[142:143]
	v_lshl_add_u64 v[144:145], v[140:141], 2, s[12:13]
	v_mov_b32_e32 v248, v144
	v_mov_b32_e32 v249, v145
	global_load_dwordx4 v[200:203], v[248:249], off
	global_load_dwordx4 v[204:207], v[248:249], off offset:16
	global_load_dwordx4 v[208:211], v[248:249], off offset:512
	global_load_dwordx4 v[212:215], v[248:249], off offset:528
	s_mov_b64 s[98:99], 0x10000
	v_lshl_add_u64 v[250:251], v[248:249], 0, s[98:99]
	global_load_dwordx4 v[216:219], v[250:251], off
	global_load_dwordx4 v[220:223], v[250:251], off offset:16
	global_load_dwordx4 v[224:227], v[250:251], off offset:512
	global_load_dwordx4 v[228:231], v[250:251], off offset:528
	s_mov_b64 s[98:99], 0x20000
	v_lshl_add_u64 v[250:251], v[248:249], 0, s[98:99]
	global_load_dwordx4 v[232:235], v[250:251], off
	global_load_dwordx4 v[236:239], v[250:251], off offset:16
	global_load_dwordx4 v[240:243], v[250:251], off offset:512
	global_load_dwordx4 v[244:247], v[250:251], off offset:528
	s_waitcnt vmcnt(8)
	s_mov_b64 s[24:25], -1
	s_and_b64 vcc, exec, s[4:5]
	v_pk_add_f32 v[126:127], v[126:127], v[202:203]
	v_pk_add_f32 v[124:125], v[124:125], v[200:201]
	v_pk_add_f32 v[122:123], v[122:123], v[206:207]
	v_pk_add_f32 v[120:121], v[120:121], v[204:205]
	global_store_dwordx4 v[144:145], v[124:127], off
	global_store_dwordx4 v[144:145], v[120:123], off offset:16
	s_cbranch_vccz .LBB0_728
	s_mov_b64 s[24:25], 0
	v_pk_add_f32 v[152:153], v[118:119], v[210:211]
	v_pk_add_f32 v[150:151], v[116:117], v[208:209]
	v_pk_add_f32 v[156:157], v[114:115], v[214:215]
	v_pk_add_f32 v[154:155], v[112:113], v[212:213]
	global_store_dwordx4 v[144:145], v[150:153], off offset:512
	global_store_dwordx4 v[144:145], v[154:157], off offset:528
.LBB0_728:
	s_andn2_b64 vcc, exec, s[24:25]
	s_cbranch_vccnz .LBB0_732
	v_cvt_pk_bf16_f32 v150, v124, v125
	v_mul_f32_e32 v125, v125, v125
	v_fmac_f32_e32 v125, v124, v124
	v_mul_f32_e32 v124, v127, v127
	v_cvt_pk_bf16_f32 v152, v120, v121
	v_fmac_f32_e32 v124, v126, v126
	v_mul_f32_e32 v121, v121, v121
	v_add_f32_e32 v124, v125, v124
	v_fmac_f32_e32 v121, v120, v120
	v_cvt_pk_bf16_f32 v151, v126, v127
	v_cvt_pk_bf16_f32 v153, v122, v123
	v_lshl_add_u64 v[154:155], v[140:141], 1, s[10:11]
	v_add_f32_e32 v120, v124, v121
	v_mul_f32_e32 v121, v123, v123
	global_store_dwordx4 v[154:155], v[150:153], off
	v_fmac_f32_e32 v121, v122, v122
	s_nop 0
	v_add_f32_e32 v150, v121, v120
	v_pk_add_f32 v[114:115], v[114:115], v[214:215]
	v_pk_add_f32 v[118:119], v[118:119], v[210:211]
	v_pk_add_f32 v[116:117], v[116:117], v[208:209]
	v_pk_add_f32 v[112:113], v[112:113], v[212:213]
	global_store_dwordx4 v[144:145], v[116:119], off offset:512
	global_store_dwordx4 v[144:145], v[112:115], off offset:528
	v_cvt_pk_bf16_f32 v123, v114, v115
	v_cvt_pk_bf16_f32 v120, v116, v117
	v_mul_f32_e32 v115, v115, v115
	v_fmac_f32_e32 v115, v114, v114
	v_mul_f32_e32 v114, v117, v117
	v_fmac_f32_e32 v114, v116, v116
	v_mul_f32_e32 v116, v119, v119
	v_cvt_pk_bf16_f32 v122, v112, v113
	v_fmac_f32_e32 v116, v118, v118
	v_mul_f32_e32 v113, v113, v113
	v_add_f32_e32 v114, v114, v116
	v_fmac_f32_e32 v113, v112, v112
	v_add_f32_e32 v112, v114, v113
	v_add_f32_e32 v112, v115, v112
	v_add_f32_e32 v112, v150, v112
	ds_bpermute_b32 v113, v180, v112
	v_cvt_pk_bf16_f32 v121, v118, v119
	global_store_dwordx4 v[154:155], v[120:123], off offset:256
	s_waitcnt lgkmcnt(0)
	v_add_f32_e32 v112, v112, v113
	ds_bpermute_b32 v113, v181, v112
	s_and_saveexec_b64 s[24:25], s[6:7]
	s_cbranch_execz .LBB0_731
	s_waitcnt lgkmcnt(0)
	v_add_f32_e32 v112, v112, v113
	v_fma_f32 v112, v112, s65, 0.5
	v_trunc_f32_e32 v112, v112
	v_mul_f32_e32 v113, 0x2f800000, v112
	v_floor_f32_e32 v113, v113
	v_fmac_f32_e32 v112, 0xcf800000, v113
	v_cvt_u32_f32_e32 v112, v112
	v_cvt_u32_f32_e32 v113, v113
	v_lshl_add_u64 v[114:115], v[138:139], 3, s[14:15]
	global_atomic_add_x2 v[114:115], v[112:113], off

.LBB0_732:
	v_or_b32_e32 v112, 16, v138
	s_waitcnt lgkmcnt(0)
	v_ashrrev_i32_e32 v113, 31, v112
	v_lshlrev_b64 v[112:113], 10, v[112:113]
	v_lshl_add_u64 v[114:115], v[112:113], 0, v[142:143]
	v_lshl_add_u64 v[112:113], v[114:115], 2, s[12:13]
	s_mov_b64 s[98:99], 0x30000
	v_lshl_add_u64 v[250:251], v[248:249], 0, s[98:99]
	global_load_dwordx4 v[200:203], v[250:251], off
	global_load_dwordx4 v[204:207], v[250:251], off offset:16
	global_load_dwordx4 v[208:211], v[250:251], off offset:512
	global_load_dwordx4 v[212:215], v[250:251], off offset:528
	s_waitcnt vmcnt(12)
	s_mov_b64 s[24:25], -1
	s_and_b64 vcc, exec, s[4:5]
	v_pk_add_f32 v[110:111], v[110:111], v[218:219]
	v_pk_add_f32 v[108:109], v[108:109], v[216:217]
	v_pk_add_f32 v[106:107], v[106:107], v[222:223]
	v_pk_add_f32 v[104:105], v[104:105], v[220:221]
	global_store_dwordx4 v[112:113], v[108:111], off
	global_store_dwordx4 v[112:113], v[104:107], off offset:16
	s_cbranch_vccz .LBB0_734
	s_mov_b64 s[24:25], 0
	v_pk_add_f32 v[118:119], v[102:103], v[226:227]
	v_pk_add_f32 v[116:117], v[100:101], v[224:225]
	v_pk_add_f32 v[122:123], v[98:99], v[230:231]
	v_pk_add_f32 v[120:121], v[96:97], v[228:229]
	global_store_dwordx4 v[112:113], v[116:119], off offset:512
	global_store_dwordx4 v[112:113], v[120:123], off offset:528
.LBB0_734:
	v_readlane_b32 s62, v254, 61
	v_readlane_b32 s66, v254, 63
	s_andn2_b64 vcc, exec, s[24:25]
	v_readlane_b32 s63, v254, 62
	v_readlane_b32 s67, v255, 0
	s_cbranch_vccnz .LBB0_738
	v_cvt_pk_bf16_f32 v116, v108, v109
	v_mul_f32_e32 v109, v109, v109
	v_fmac_f32_e32 v109, v108, v108
	v_mul_f32_e32 v108, v111, v111
	v_cvt_pk_bf16_f32 v118, v104, v105
	v_fmac_f32_e32 v108, v110, v110
	v_mul_f32_e32 v105, v105, v105
	v_add_f32_e32 v108, v109, v108
	v_fmac_f32_e32 v105, v104, v104
	v_cvt_pk_bf16_f32 v117, v110, v111
	v_cvt_pk_bf16_f32 v119, v106, v107
	v_lshl_add_u64 v[114:115], v[114:115], 1, s[10:11]
	v_add_f32_e32 v104, v108, v105
	v_mul_f32_e32 v105, v107, v107
	global_store_dwordx4 v[114:115], v[116:119], off
	v_fmac_f32_e32 v105, v106, v106
	s_nop 0
	v_add_f32_e32 v116, v105, v104
	v_pk_add_f32 v[98:99], v[98:99], v[230:231]
	v_pk_add_f32 v[102:103], v[102:103], v[226:227]
	v_pk_add_f32 v[100:101], v[100:101], v[224:225]
	v_pk_add_f32 v[96:97], v[96:97], v[228:229]
	global_store_dwordx4 v[112:113], v[100:103], off offset:512
	global_store_dwordx4 v[112:113], v[96:99], off offset:528
	v_cvt_pk_bf16_f32 v107, v98, v99
	v_cvt_pk_bf16_f32 v104, v100, v101
	v_mul_f32_e32 v99, v99, v99
	v_fmac_f32_e32 v99, v98, v98
	v_mul_f32_e32 v98, v101, v101
	v_fmac_f32_e32 v98, v100, v100
	v_mul_f32_e32 v100, v103, v103
	v_cvt_pk_bf16_f32 v106, v96, v97
	v_fmac_f32_e32 v100, v102, v102
	v_mul_f32_e32 v97, v97, v97
	v_add_f32_e32 v98, v98, v100
	v_fmac_f32_e32 v97, v96, v96
	v_add_f32_e32 v96, v98, v97
	v_add_f32_e32 v96, v99, v96
	v_add_f32_e32 v96, v116, v96
	ds_bpermute_b32 v97, v180, v96
	v_cvt_pk_bf16_f32 v105, v102, v103
	global_store_dwordx4 v[114:115], v[104:107], off offset:256
	s_waitcnt lgkmcnt(0)
	v_add_f32_e32 v96, v96, v97
	ds_bpermute_b32 v97, v181, v96
	s_and_saveexec_b64 s[24:25], s[6:7]
	s_cbranch_execz .LBB0_737
	s_waitcnt lgkmcnt(0)
	v_add_f32_e32 v96, v96, v97
	v_fma_f32 v96, v96, s65, 0.5
	v_trunc_f32_e32 v96, v96
	v_mul_f32_e32 v97, 0x2f800000, v96
	v_floor_f32_e32 v97, v97
	v_fmac_f32_e32 v96, 0xcf800000, v97
	v_cvt_u32_f32_e32 v96, v96
	v_cvt_u32_f32_e32 v97, v97
	v_lshl_add_u64 v[98:99], v[138:139], 3, s[14:15]
	global_atomic_add_x2 v[98:99], v[96:97], off offset:128

.LBB0_738:
	v_or_b32_e32 v96, 32, v138
	s_waitcnt lgkmcnt(0)
	v_ashrrev_i32_e32 v97, 31, v96
	v_lshlrev_b64 v[96:97], 10, v[96:97]
	v_lshl_add_u64 v[98:99], v[96:97], 0, v[142:143]
	v_lshl_add_u64 v[96:97], v[98:99], 2, s[12:13]
	s_mov_b64 s[98:99], 0x80000
	v_lshl_add_u64 v[250:251], v[248:249], 0, s[98:99]
	global_load_dwordx4 v[216:219], v[250:251], off
	global_load_dwordx4 v[220:223], v[250:251], off offset:16
	global_load_dwordx4 v[224:227], v[250:251], off offset:512
	global_load_dwordx4 v[228:231], v[250:251], off offset:528
	s_waitcnt vmcnt(16)
	s_mov_b64 s[24:25], -1
	s_and_b64 vcc, exec, s[4:5]
	v_pk_add_f32 v[94:95], v[94:95], v[234:235]
	v_pk_add_f32 v[92:93], v[92:93], v[232:233]
	v_pk_add_f32 v[90:91], v[90:91], v[238:239]
	v_pk_add_f32 v[88:89], v[88:89], v[236:237]
	global_store_dwordx4 v[96:97], v[92:95], off
	global_store_dwordx4 v[96:97], v[88:91], off offset:16
	s_cbranch_vccz .LBB0_740
	s_mov_b64 s[24:25], 0
	v_pk_add_f32 v[102:103], v[86:87], v[242:243]
	v_pk_add_f32 v[100:101], v[84:85], v[240:241]
	v_pk_add_f32 v[106:107], v[82:83], v[246:247]
	v_pk_add_f32 v[104:105], v[80:81], v[244:245]
	global_store_dwordx4 v[96:97], v[100:103], off offset:512
	global_store_dwordx4 v[96:97], v[104:107], off offset:528
.LBB0_740:
	s_andn2_b64 vcc, exec, s[24:25]
	s_cbranch_vccnz .LBB0_744
	v_cvt_pk_bf16_f32 v100, v92, v93
	v_mul_f32_e32 v93, v93, v93
	v_fmac_f32_e32 v93, v92, v92
	v_mul_f32_e32 v92, v95, v95
	v_cvt_pk_bf16_f32 v102, v88, v89
	v_fmac_f32_e32 v92, v94, v94
	v_mul_f32_e32 v89, v89, v89
	v_add_f32_e32 v92, v93, v92
	v_fmac_f32_e32 v89, v88, v88
	v_cvt_pk_bf16_f32 v101, v94, v95
	v_cvt_pk_bf16_f32 v103, v90, v91
	v_lshl_add_u64 v[98:99], v[98:99], 1, s[10:11]
	v_add_f32_e32 v88, v92, v89
	v_mul_f32_e32 v89, v91, v91
	global_store_dwordx4 v[98:99], v[100:103], off
	v_fmac_f32_e32 v89, v90, v90
	s_nop 0
	v_add_f32_e32 v100, v89, v88
	v_pk_add_f32 v[82:83], v[82:83], v[246:247]
	v_pk_add_f32 v[86:87], v[86:87], v[242:243]
	v_pk_add_f32 v[84:85], v[84:85], v[240:241]
	v_pk_add_f32 v[80:81], v[80:81], v[244:245]
	global_store_dwordx4 v[96:97], v[84:87], off offset:512
	global_store_dwordx4 v[96:97], v[80:83], off offset:528
	v_cvt_pk_bf16_f32 v91, v82, v83
	v_cvt_pk_bf16_f32 v88, v84, v85
	v_mul_f32_e32 v83, v83, v83
	v_fmac_f32_e32 v83, v82, v82
	v_mul_f32_e32 v82, v85, v85
	v_fmac_f32_e32 v82, v84, v84
	v_mul_f32_e32 v84, v87, v87
	v_cvt_pk_bf16_f32 v90, v80, v81
	v_fmac_f32_e32 v84, v86, v86
	v_mul_f32_e32 v81, v81, v81
	v_add_f32_e32 v82, v82, v84
	v_fmac_f32_e32 v81, v80, v80
	v_add_f32_e32 v80, v82, v81
	v_add_f32_e32 v80, v83, v80
	v_add_f32_e32 v80, v100, v80
	ds_bpermute_b32 v81, v180, v80
	v_cvt_pk_bf16_f32 v89, v86, v87
	global_store_dwordx4 v[98:99], v[88:91], off offset:256
	s_waitcnt lgkmcnt(0)
	v_add_f32_e32 v80, v80, v81
	ds_bpermute_b32 v81, v181, v80
	s_and_saveexec_b64 s[24:25], s[6:7]
	s_cbranch_execz .LBB0_743
	s_waitcnt lgkmcnt(0)
	v_add_f32_e32 v80, v80, v81
	v_fma_f32 v80, v80, s65, 0.5
	v_trunc_f32_e32 v80, v80
	v_mul_f32_e32 v81, 0x2f800000, v80
	v_floor_f32_e32 v81, v81
	v_fmac_f32_e32 v80, 0xcf800000, v81
	v_cvt_u32_f32_e32 v80, v80
	v_cvt_u32_f32_e32 v81, v81
	v_lshl_add_u64 v[82:83], v[138:139], 3, s[14:15]
	global_atomic_add_x2 v[82:83], v[80:81], off offset:256

.LBB0_744:
	v_or_b32_e32 v80, 48, v138
	s_waitcnt lgkmcnt(0)
	v_ashrrev_i32_e32 v81, 31, v80
	v_lshlrev_b64 v[80:81], 10, v[80:81]
	v_lshl_add_u64 v[82:83], v[80:81], 0, v[142:143]
	v_lshl_add_u64 v[80:81], v[82:83], 2, s[12:13]
	s_mov_b64 s[98:99], 0x90000
	v_lshl_add_u64 v[250:251], v[248:249], 0, s[98:99]
	global_load_dwordx4 v[232:235], v[250:251], off
	global_load_dwordx4 v[236:239], v[250:251], off offset:16
	global_load_dwordx4 v[240:243], v[250:251], off offset:512
	global_load_dwordx4 v[244:247], v[250:251], off offset:528
	s_waitcnt vmcnt(16)
	s_mov_b64 s[24:25], -1
	s_and_b64 vcc, exec, s[4:5]
	v_pk_add_f32 v[78:79], v[78:79], v[202:203]
	v_pk_add_f32 v[76:77], v[76:77], v[200:201]
	v_pk_add_f32 v[74:75], v[74:75], v[206:207]
	v_pk_add_f32 v[72:73], v[72:73], v[204:205]
	global_store_dwordx4 v[80:81], v[76:79], off
	global_store_dwordx4 v[80:81], v[72:75], off offset:16
	s_cbranch_vccz .LBB0_746
	s_mov_b64 s[24:25], 0
	v_pk_add_f32 v[86:87], v[70:71], v[210:211]
	v_pk_add_f32 v[84:85], v[68:69], v[208:209]
	v_pk_add_f32 v[90:91], v[66:67], v[214:215]
	v_pk_add_f32 v[88:89], v[64:65], v[212:213]
	global_store_dwordx4 v[80:81], v[84:87], off offset:512
	global_store_dwordx4 v[80:81], v[88:91], off offset:528
.LBB0_746:
	s_andn2_b64 vcc, exec, s[24:25]
	s_cbranch_vccnz .LBB0_750
	v_cvt_pk_bf16_f32 v84, v76, v77
	v_mul_f32_e32 v77, v77, v77
	v_fmac_f32_e32 v77, v76, v76
	v_mul_f32_e32 v76, v79, v79
	v_cvt_pk_bf16_f32 v86, v72, v73
	v_fmac_f32_e32 v76, v78, v78
	v_mul_f32_e32 v73, v73, v73
	v_add_f32_e32 v76, v77, v76
	v_fmac_f32_e32 v73, v72, v72
	v_cvt_pk_bf16_f32 v85, v78, v79
	v_cvt_pk_bf16_f32 v87, v74, v75
	v_lshl_add_u64 v[82:83], v[82:83], 1, s[10:11]
	v_add_f32_e32 v72, v76, v73
	v_mul_f32_e32 v73, v75, v75
	global_store_dwordx4 v[82:83], v[84:87], off
	v_fmac_f32_e32 v73, v74, v74
	s_nop 0
	v_add_f32_e32 v84, v73, v72
	v_pk_add_f32 v[66:67], v[66:67], v[214:215]
	v_pk_add_f32 v[70:71], v[70:71], v[210:211]
	v_pk_add_f32 v[68:69], v[68:69], v[208:209]
	v_pk_add_f32 v[64:65], v[64:65], v[212:213]
	global_store_dwordx4 v[80:81], v[68:71], off offset:512
	global_store_dwordx4 v[80:81], v[64:67], off offset:528
	v_cvt_pk_bf16_f32 v75, v66, v67
	v_cvt_pk_bf16_f32 v72, v68, v69
	v_mul_f32_e32 v67, v67, v67
	v_fmac_f32_e32 v67, v66, v66
	v_mul_f32_e32 v66, v69, v69
	v_fmac_f32_e32 v66, v68, v68
	v_mul_f32_e32 v68, v71, v71
	v_cvt_pk_bf16_f32 v74, v64, v65
	v_fmac_f32_e32 v68, v70, v70
	v_mul_f32_e32 v65, v65, v65
	v_add_f32_e32 v66, v66, v68
	v_fmac_f32_e32 v65, v64, v64
	v_add_f32_e32 v64, v66, v65
	v_add_f32_e32 v64, v67, v64
	v_add_f32_e32 v64, v84, v64
	ds_bpermute_b32 v65, v180, v64
	v_cvt_pk_bf16_f32 v73, v70, v71
	global_store_dwordx4 v[82:83], v[72:75], off offset:256
	s_waitcnt lgkmcnt(0)
	v_add_f32_e32 v64, v64, v65
	ds_bpermute_b32 v65, v181, v64
	s_and_saveexec_b64 s[24:25], s[6:7]
	s_cbranch_execz .LBB0_749
	s_waitcnt lgkmcnt(0)
	v_add_f32_e32 v64, v64, v65
	v_fma_f32 v64, v64, s65, 0.5
	v_trunc_f32_e32 v64, v64
	v_mul_f32_e32 v65, 0x2f800000, v64
	v_floor_f32_e32 v65, v65
	v_fmac_f32_e32 v64, 0xcf800000, v65
	v_cvt_u32_f32_e32 v64, v64
	v_cvt_u32_f32_e32 v65, v65
	v_lshl_add_u64 v[66:67], v[138:139], 3, s[14:15]
	global_atomic_add_x2 v[66:67], v[64:65], off offset:384

.LBB0_750:
	s_mov_b64 s[24:25], 0x20000
	v_lshl_add_u64 v[66:67], v[140:141], 0, s[24:25]
	s_waitcnt lgkmcnt(0)
	v_lshl_add_u64 v[64:65], v[66:67], 2, s[12:13]
	s_mov_b64 s[98:99], 0xa0000
	v_lshl_add_u64 v[250:251], v[248:249], 0, s[98:99]
	global_load_dwordx4 v[200:203], v[250:251], off
	global_load_dwordx4 v[204:207], v[250:251], off offset:16
	global_load_dwordx4 v[208:211], v[250:251], off offset:512
	global_load_dwordx4 v[212:215], v[250:251], off offset:528
	s_waitcnt vmcnt(16)
	s_mov_b64 s[24:25], -1
	s_and_b64 vcc, exec, s[4:5]
	v_pk_add_f32 v[62:63], v[62:63], v[218:219]
	v_pk_add_f32 v[60:61], v[60:61], v[216:217]
	v_pk_add_f32 v[58:59], v[58:59], v[222:223]
	v_pk_add_f32 v[56:57], v[56:57], v[220:221]
	global_store_dwordx4 v[64:65], v[60:63], off
	global_store_dwordx4 v[64:65], v[56:59], off offset:16
	s_cbranch_vccz .LBB0_752
	s_mov_b64 s[24:25], 0
	v_pk_add_f32 v[70:71], v[54:55], v[226:227]
	v_pk_add_f32 v[68:69], v[52:53], v[224:225]
	v_pk_add_f32 v[74:75], v[50:51], v[230:231]
	v_pk_add_f32 v[72:73], v[48:49], v[228:229]
	global_store_dwordx4 v[64:65], v[68:71], off offset:512
	global_store_dwordx4 v[64:65], v[72:75], off offset:528
.LBB0_752:
	s_andn2_b64 vcc, exec, s[24:25]
	s_cbranch_vccnz .LBB0_756
	v_cvt_pk_bf16_f32 v68, v60, v61
	v_mul_f32_e32 v61, v61, v61
	v_fmac_f32_e32 v61, v60, v60
	v_mul_f32_e32 v60, v63, v63
	v_cvt_pk_bf16_f32 v70, v56, v57
	v_fmac_f32_e32 v60, v62, v62
	v_mul_f32_e32 v57, v57, v57
	v_add_f32_e32 v60, v61, v60
	v_fmac_f32_e32 v57, v56, v56
	v_cvt_pk_bf16_f32 v69, v62, v63
	v_cvt_pk_bf16_f32 v71, v58, v59
	v_lshl_add_u64 v[66:67], v[66:67], 1, s[10:11]
	v_add_f32_e32 v56, v60, v57
	v_mul_f32_e32 v57, v59, v59
	global_store_dwordx4 v[66:67], v[68:71], off
	v_fmac_f32_e32 v57, v58, v58
	s_nop 0
	v_add_f32_e32 v68, v57, v56
	v_pk_add_f32 v[50:51], v[50:51], v[230:231]
	v_pk_add_f32 v[54:55], v[54:55], v[226:227]
	v_pk_add_f32 v[52:53], v[52:53], v[224:225]
	v_pk_add_f32 v[48:49], v[48:49], v[228:229]
	global_store_dwordx4 v[64:65], v[52:55], off offset:512
	global_store_dwordx4 v[64:65], v[48:51], off offset:528
	v_cvt_pk_bf16_f32 v59, v50, v51
	v_cvt_pk_bf16_f32 v56, v52, v53
	v_mul_f32_e32 v51, v51, v51
	v_fmac_f32_e32 v51, v50, v50
	v_mul_f32_e32 v50, v53, v53
	v_fmac_f32_e32 v50, v52, v52
	v_mul_f32_e32 v52, v55, v55
	v_cvt_pk_bf16_f32 v58, v48, v49
	v_fmac_f32_e32 v52, v54, v54
	v_mul_f32_e32 v49, v49, v49
	v_add_f32_e32 v50, v50, v52
	v_fmac_f32_e32 v49, v48, v48
	v_add_f32_e32 v48, v50, v49
	v_add_f32_e32 v48, v51, v48
	v_add_f32_e32 v48, v68, v48
	ds_bpermute_b32 v49, v180, v48
	v_cvt_pk_bf16_f32 v57, v54, v55
	global_store_dwordx4 v[66:67], v[56:59], off offset:256
	s_waitcnt lgkmcnt(0)
	v_add_f32_e32 v48, v48, v49
	ds_bpermute_b32 v49, v181, v48
	s_and_saveexec_b64 s[24:25], s[6:7]
	s_cbranch_execz .LBB0_755
	s_waitcnt lgkmcnt(0)
	v_add_f32_e32 v48, v48, v49
	v_fma_f32 v48, v48, s65, 0.5
	v_trunc_f32_e32 v48, v48
	v_mul_f32_e32 v49, 0x2f800000, v48
	v_floor_f32_e32 v49, v49
	v_fmac_f32_e32 v48, 0xcf800000, v49
	v_cvt_u32_f32_e32 v48, v48
	v_cvt_u32_f32_e32 v49, v49
	v_lshl_add_u64 v[50:51], v[138:139], 3, s[14:15]
	global_atomic_add_x2 v[50:51], v[48:49], off offset:1024

.LBB0_756:
	s_mov_b64 s[24:25], 0x24000
	v_lshl_add_u64 v[50:51], v[140:141], 0, s[24:25]
	s_waitcnt lgkmcnt(0)
	v_lshl_add_u64 v[48:49], v[50:51], 2, s[12:13]
	s_mov_b64 s[98:99], 0xb0000
	v_lshl_add_u64 v[250:251], v[248:249], 0, s[98:99]
	global_load_dwordx4 v[216:219], v[250:251], off
	global_load_dwordx4 v[220:223], v[250:251], off offset:16
	global_load_dwordx4 v[224:227], v[250:251], off offset:512
	global_load_dwordx4 v[228:231], v[250:251], off offset:528
	s_waitcnt vmcnt(16)
	s_mov_b64 s[24:25], -1
	s_and_b64 vcc, exec, s[4:5]
	v_pk_add_f32 v[46:47], v[46:47], v[234:235]
	v_pk_add_f32 v[44:45], v[44:45], v[232:233]
	v_pk_add_f32 v[42:43], v[42:43], v[238:239]
	v_pk_add_f32 v[40:41], v[40:41], v[236:237]
	global_store_dwordx4 v[48:49], v[44:47], off
	global_store_dwordx4 v[48:49], v[40:43], off offset:16
	s_cbranch_vccz .LBB0_758
	s_mov_b64 s[24:25], 0
	v_pk_add_f32 v[54:55], v[38:39], v[242:243]
	v_pk_add_f32 v[52:53], v[36:37], v[240:241]
	v_pk_add_f32 v[58:59], v[34:35], v[246:247]
	v_pk_add_f32 v[56:57], v[32:33], v[244:245]
	global_store_dwordx4 v[48:49], v[52:55], off offset:512
	global_store_dwordx4 v[48:49], v[56:59], off offset:528
.LBB0_758:
	s_andn2_b64 vcc, exec, s[24:25]
	s_cbranch_vccnz .LBB0_762
	v_cvt_pk_bf16_f32 v52, v44, v45
	v_mul_f32_e32 v45, v45, v45
	v_fmac_f32_e32 v45, v44, v44
	v_mul_f32_e32 v44, v47, v47
	v_cvt_pk_bf16_f32 v54, v40, v41
	v_fmac_f32_e32 v44, v46, v46
	v_mul_f32_e32 v41, v41, v41
	v_add_f32_e32 v44, v45, v44
	v_fmac_f32_e32 v41, v40, v40
	v_cvt_pk_bf16_f32 v53, v46, v47
	v_cvt_pk_bf16_f32 v55, v42, v43
	v_lshl_add_u64 v[50:51], v[50:51], 1, s[10:11]
	v_add_f32_e32 v40, v44, v41
	v_mul_f32_e32 v41, v43, v43
	global_store_dwordx4 v[50:51], v[52:55], off
	v_fmac_f32_e32 v41, v42, v42
	s_nop 0
	v_add_f32_e32 v52, v41, v40
	v_pk_add_f32 v[34:35], v[34:35], v[246:247]
	v_pk_add_f32 v[38:39], v[38:39], v[242:243]
	v_pk_add_f32 v[36:37], v[36:37], v[240:241]
	v_pk_add_f32 v[32:33], v[32:33], v[244:245]
	global_store_dwordx4 v[48:49], v[36:39], off offset:512
	global_store_dwordx4 v[48:49], v[32:35], off offset:528
	v_cvt_pk_bf16_f32 v43, v34, v35
	v_cvt_pk_bf16_f32 v40, v36, v37
	v_mul_f32_e32 v35, v35, v35
	v_fmac_f32_e32 v35, v34, v34
	v_mul_f32_e32 v34, v37, v37
	v_fmac_f32_e32 v34, v36, v36
	v_mul_f32_e32 v36, v39, v39
	v_cvt_pk_bf16_f32 v42, v32, v33
	v_fmac_f32_e32 v36, v38, v38
	v_mul_f32_e32 v33, v33, v33
	v_add_f32_e32 v34, v34, v36
	v_fmac_f32_e32 v33, v32, v32
	v_add_f32_e32 v32, v34, v33
	v_add_f32_e32 v32, v35, v32
	v_add_f32_e32 v32, v52, v32
	ds_bpermute_b32 v33, v180, v32
	v_cvt_pk_bf16_f32 v41, v38, v39
	global_store_dwordx4 v[50:51], v[40:43], off offset:256
	s_waitcnt lgkmcnt(0)
	v_add_f32_e32 v32, v32, v33
	ds_bpermute_b32 v33, v181, v32
	s_and_saveexec_b64 s[24:25], s[6:7]
	s_cbranch_execz .LBB0_761
	s_waitcnt lgkmcnt(0)
	v_add_f32_e32 v32, v32, v33
	v_fma_f32 v32, v32, s65, 0.5
	v_trunc_f32_e32 v32, v32
	v_mul_f32_e32 v33, 0x2f800000, v32
	v_floor_f32_e32 v33, v33
	v_fmac_f32_e32 v32, 0xcf800000, v33
	v_cvt_u32_f32_e32 v32, v32
	v_cvt_u32_f32_e32 v33, v33
	v_lshl_add_u64 v[34:35], v[138:139], 3, s[14:15]
	global_atomic_add_x2 v[34:35], v[32:33], off offset:1152

.LBB0_762:
	s_mov_b64 s[24:25], 0x28000
	v_lshl_add_u64 v[34:35], v[140:141], 0, s[24:25]
	s_waitcnt lgkmcnt(0)
	v_lshl_add_u64 v[32:33], v[34:35], 2, s[12:13]
	s_waitcnt vmcnt(12)
	s_mov_b64 s[24:25], -1
	s_and_b64 vcc, exec, s[4:5]
	v_pk_add_f32 v[30:31], v[30:31], v[202:203]
	v_pk_add_f32 v[28:29], v[28:29], v[200:201]
	v_pk_add_f32 v[26:27], v[26:27], v[206:207]
	v_pk_add_f32 v[24:25], v[24:25], v[204:205]
	global_store_dwordx4 v[32:33], v[28:31], off
	global_store_dwordx4 v[32:33], v[24:27], off offset:16
	s_cbranch_vccz .LBB0_764
	s_mov_b64 s[24:25], 0
	v_pk_add_f32 v[38:39], v[22:23], v[210:211]
	v_pk_add_f32 v[36:37], v[20:21], v[208:209]
	v_pk_add_f32 v[42:43], v[18:19], v[214:215]
	v_pk_add_f32 v[40:41], v[16:17], v[212:213]
	global_store_dwordx4 v[32:33], v[36:39], off offset:512
	global_store_dwordx4 v[32:33], v[40:43], off offset:528
.LBB0_764:
	s_andn2_b64 vcc, exec, s[24:25]
	s_cbranch_vccnz .LBB0_768
	v_cvt_pk_bf16_f32 v36, v28, v29
	v_mul_f32_e32 v29, v29, v29
	v_fmac_f32_e32 v29, v28, v28
	v_mul_f32_e32 v28, v31, v31
	v_cvt_pk_bf16_f32 v38, v24, v25
	v_fmac_f32_e32 v28, v30, v30
	v_mul_f32_e32 v25, v25, v25
	v_add_f32_e32 v28, v29, v28
	v_fmac_f32_e32 v25, v24, v24
	v_cvt_pk_bf16_f32 v37, v30, v31
	v_cvt_pk_bf16_f32 v39, v26, v27
	v_lshl_add_u64 v[34:35], v[34:35], 1, s[10:11]
	v_add_f32_e32 v24, v28, v25
	v_mul_f32_e32 v25, v27, v27
	global_store_dwordx4 v[34:35], v[36:39], off
	v_fmac_f32_e32 v25, v26, v26
	s_nop 0
	v_add_f32_e32 v36, v25, v24
	v_pk_add_f32 v[18:19], v[18:19], v[214:215]
	v_pk_add_f32 v[22:23], v[22:23], v[210:211]
	v_pk_add_f32 v[20:21], v[20:21], v[208:209]
	v_pk_add_f32 v[16:17], v[16:17], v[212:213]
	global_store_dwordx4 v[32:33], v[20:23], off offset:512
	global_store_dwordx4 v[32:33], v[16:19], off offset:528
	v_cvt_pk_bf16_f32 v27, v18, v19
	v_cvt_pk_bf16_f32 v24, v20, v21
	v_mul_f32_e32 v19, v19, v19
	v_fmac_f32_e32 v19, v18, v18
	v_mul_f32_e32 v18, v21, v21
	v_fmac_f32_e32 v18, v20, v20
	v_mul_f32_e32 v20, v23, v23
	v_cvt_pk_bf16_f32 v26, v16, v17
	v_fmac_f32_e32 v20, v22, v22
	v_mul_f32_e32 v17, v17, v17
	v_add_f32_e32 v18, v18, v20
	v_fmac_f32_e32 v17, v16, v16
	v_add_f32_e32 v16, v18, v17
	v_add_f32_e32 v16, v19, v16
	v_add_f32_e32 v16, v36, v16
	ds_bpermute_b32 v17, v180, v16
	v_cvt_pk_bf16_f32 v25, v22, v23
	global_store_dwordx4 v[34:35], v[24:27], off offset:256
	s_waitcnt lgkmcnt(0)
	v_add_f32_e32 v16, v16, v17
	ds_bpermute_b32 v17, v181, v16
	s_and_saveexec_b64 s[24:25], s[6:7]
	s_cbranch_execz .LBB0_767
	s_waitcnt lgkmcnt(0)
	v_add_f32_e32 v16, v16, v17
	v_fma_f32 v16, v16, s65, 0.5
	v_trunc_f32_e32 v16, v16
	v_mul_f32_e32 v17, 0x2f800000, v16
	v_floor_f32_e32 v17, v17
	v_fmac_f32_e32 v16, 0xcf800000, v17
	v_cvt_u32_f32_e32 v16, v16
	v_cvt_u32_f32_e32 v17, v17
	v_lshl_add_u64 v[18:19], v[138:139], 3, s[14:15]
	global_atomic_add_x2 v[18:19], v[16:17], off offset:1280

.LBB0_768:
	s_mov_b64 s[24:25], 0x2c000
	v_lshl_add_u64 v[18:19], v[140:141], 0, s[24:25]
	s_waitcnt lgkmcnt(0)
	v_lshl_add_u64 v[16:17], v[18:19], 2, s[12:13]
	s_waitcnt vmcnt(8)
	s_mov_b64 s[24:25], -1
	s_and_b64 vcc, exec, s[4:5]
	v_pk_add_f32 v[14:15], v[14:15], v[218:219]
	v_pk_add_f32 v[12:13], v[12:13], v[216:217]
	v_pk_add_f32 v[10:11], v[10:11], v[222:223]
	v_pk_add_f32 v[8:9], v[8:9], v[220:221]
	global_store_dwordx4 v[16:17], v[12:15], off
	global_store_dwordx4 v[16:17], v[8:11], off offset:16
	s_cbranch_vccz .LBB0_770
	s_mov_b64 s[24:25], 0
	v_pk_add_f32 v[22:23], v[6:7], v[226:227]
	v_pk_add_f32 v[20:21], v[4:5], v[224:225]
	v_pk_add_f32 v[26:27], v[2:3], v[230:231]
	v_pk_add_f32 v[24:25], v[0:1], v[228:229]
	global_store_dwordx4 v[16:17], v[20:23], off offset:512
	global_store_dwordx4 v[16:17], v[24:27], off offset:528
.LBB0_770:
	s_andn2_b64 vcc, exec, s[24:25]
	s_cbranch_vccnz .LBB0_717
	v_cvt_pk_bf16_f32 v20, v12, v13
	v_mul_f32_e32 v13, v13, v13
	v_fmac_f32_e32 v13, v12, v12
	v_mul_f32_e32 v12, v15, v15
	v_cvt_pk_bf16_f32 v22, v8, v9
	v_fmac_f32_e32 v12, v14, v14
	v_mul_f32_e32 v9, v9, v9
	v_add_f32_e32 v12, v13, v12
	v_fmac_f32_e32 v9, v8, v8
	v_cvt_pk_bf16_f32 v21, v14, v15
	v_cvt_pk_bf16_f32 v23, v10, v11
	v_lshl_add_u64 v[18:19], v[18:19], 1, s[10:11]
	v_add_f32_e32 v8, v12, v9
	v_mul_f32_e32 v9, v11, v11
	global_store_dwordx4 v[18:19], v[20:23], off
	v_fmac_f32_e32 v9, v10, v10
	s_nop 0
	v_add_f32_e32 v20, v9, v8
	v_pk_add_f32 v[2:3], v[2:3], v[230:231]
	v_pk_add_f32 v[6:7], v[6:7], v[226:227]
	v_pk_add_f32 v[4:5], v[4:5], v[224:225]
	v_pk_add_f32 v[0:1], v[0:1], v[228:229]
	global_store_dwordx4 v[16:17], v[4:7], off offset:512
	global_store_dwordx4 v[16:17], v[0:3], off offset:528
	v_cvt_pk_bf16_f32 v11, v2, v3
	v_cvt_pk_bf16_f32 v8, v4, v5
	v_mul_f32_e32 v3, v3, v3
	v_fmac_f32_e32 v3, v2, v2
	v_mul_f32_e32 v2, v5, v5
	v_fmac_f32_e32 v2, v4, v4
	v_mul_f32_e32 v4, v7, v7
	v_cvt_pk_bf16_f32 v10, v0, v1
	v_fmac_f32_e32 v4, v6, v6
	v_mul_f32_e32 v1, v1, v1
	v_add_f32_e32 v2, v2, v4
	v_fmac_f32_e32 v1, v0, v0
	v_add_f32_e32 v0, v2, v1
	v_add_f32_e32 v0, v3, v0
	v_add_f32_e32 v0, v20, v0
	ds_bpermute_b32 v1, v180, v0
	v_cvt_pk_bf16_f32 v9, v6, v7
	global_store_dwordx4 v[18:19], v[8:11], off offset:256
	s_waitcnt lgkmcnt(0)
	v_add_f32_e32 v0, v0, v1
	ds_bpermute_b32 v1, v181, v0
	s_and_saveexec_b64 s[24:25], s[6:7]
	s_cbranch_execz .LBB0_716
	s_waitcnt lgkmcnt(0)
	v_add_f32_e32 v0, v0, v1
	v_fma_f32 v0, v0, s65, 0.5
	v_trunc_f32_e32 v0, v0
	v_mul_f32_e32 v1, 0x2f800000, v0
	v_floor_f32_e32 v1, v1
	v_fmac_f32_e32 v0, 0xcf800000, v1
	v_cvt_u32_f32_e32 v0, v0
	v_cvt_u32_f32_e32 v1, v1
	v_lshl_add_u64 v[2:3], v[138:139], 3, s[14:15]
	global_atomic_add_x2 v[2:3], v[0:1], off offset:1408
	s_branch .LBB0_716
